# K-loop MFMAs reordered: both k-steps of one accumulator issued back to back
# speedup vs baseline: 1.0263x; 1.0263x over previous
.LBB0_262:
	s_add_i32 vcc_lo, s38, 2
	s_add_u32 s39, s10, 0xfff00080
	s_addc_u32 s66, s11, -1
	s_add_i32 s67, 0, 0x10000
	s_cmp_eq_u32 s35, s38
	s_cselect_b32 s87, s53, s66
	s_cselect_b32 s86, s52, s39
	s_cselect_b32 s39, s13, s49
	s_cselect_b32 s38, s15, s40
	s_add_i32 vcc_hi, 0, 0x14000
	v_add_u32_e32 v142, s67, v1
	v_add_u32_e32 v180, vcc_hi, v1
	ds_read_b128 v[130:133], v142
	ds_read_b128 v[134:137], v142 offset:1024
	ds_read_b128 v[138:141], v142 offset:2048
	ds_read_b128 v[142:145], v142 offset:3072
	ds_read_b128 v[168:171], v180
	ds_read_b128 v[172:175], v180 offset:1024
	ds_read_b128 v[176:179], v180 offset:2048
	ds_read_b128 v[180:183], v180 offset:3072
	v_lshl_add_u64 v[184:185], s[10:11], 0, v[164:165]
	s_add_i32 m0, s85, 0xc000
	ds_read_b128 v[198:201], v197
	ds_read_b128 v[202:205], v197 offset:1024
	ds_read_b128 v[206:209], v197 offset:2048
	ds_read_b128 v[210:213], v197 offset:3072
	ds_read_b128 v[214:217], v197 offset:4096
	ds_read_b128 v[218:221], v197 offset:5120
	ds_read_b128 v[222:225], v197 offset:6144
	ds_read_b128 v[226:229], v197 offset:7168
	global_load_lds_dwordx4 v[184:185], off
	v_lshl_add_u64 v[184:185], s[10:11], 0, v[166:167]
	s_add_i32 m0, s85, 0xe000
	s_nop 0
	global_load_lds_dwordx4 v[184:185], off
	s_waitcnt vmcnt(8)
	s_waitcnt lgkmcnt(0)
	s_barrier
	s_setprio 1
	s_waitcnt lgkmcnt(0)
	v_mfma_f32_16x16x32_bf16 v[114:117], v[130:133], v[198:201], v[114:117]
	v_mfma_f32_16x16x32_bf16 v[114:117], v[134:137], v[202:205], v[114:117]
	v_mfma_f32_16x16x32_bf16 v[118:121], v[138:141], v[198:201], v[118:121]
	v_mfma_f32_16x16x32_bf16 v[118:121], v[142:145], v[202:205], v[118:121]
	v_mfma_f32_16x16x32_bf16 v[102:105], v[130:133], v[206:209], v[102:105]
	v_mfma_f32_16x16x32_bf16 v[102:105], v[134:137], v[210:213], v[102:105]
	v_mfma_f32_16x16x32_bf16 v[98:101], v[138:141], v[206:209], v[98:101]
	v_mfma_f32_16x16x32_bf16 v[98:101], v[142:145], v[210:213], v[98:101]
	v_mfma_f32_16x16x32_bf16 v[86:89], v[130:133], v[214:217], v[86:89]
	v_mfma_f32_16x16x32_bf16 v[86:89], v[134:137], v[218:221], v[86:89]
	v_mfma_f32_16x16x32_bf16 v[82:85], v[138:141], v[214:217], v[82:85]
	v_mfma_f32_16x16x32_bf16 v[82:85], v[142:145], v[218:221], v[82:85]
	v_mfma_f32_16x16x32_bf16 v[54:57], v[130:133], v[222:225], v[54:57]
	v_mfma_f32_16x16x32_bf16 v[54:57], v[134:137], v[226:229], v[54:57]
	v_mfma_f32_16x16x32_bf16 v[50:53], v[138:141], v[222:225], v[50:53]
	v_mfma_f32_16x16x32_bf16 v[50:53], v[142:145], v[226:229], v[50:53]
	s_setprio 0
	s_setprio 1
	v_mfma_f32_16x16x32_bf16 v[126:129], v[168:171], v[198:201], v[126:129]
	v_mfma_f32_16x16x32_bf16 v[126:129], v[172:175], v[202:205], v[126:129]
	v_mfma_f32_16x16x32_bf16 v[122:125], v[176:179], v[198:201], v[122:125]
	v_mfma_f32_16x16x32_bf16 v[122:125], v[180:183], v[202:205], v[122:125]
	v_mfma_f32_16x16x32_bf16 v[110:113], v[168:171], v[206:209], v[110:113]
	v_mfma_f32_16x16x32_bf16 v[110:113], v[172:175], v[210:213], v[110:113]
	v_mfma_f32_16x16x32_bf16 v[106:109], v[176:179], v[206:209], v[106:109]
	v_mfma_f32_16x16x32_bf16 v[106:109], v[180:183], v[210:213], v[106:109]
	v_mfma_f32_16x16x32_bf16 v[94:97], v[168:171], v[214:217], v[94:97]
	v_mfma_f32_16x16x32_bf16 v[94:97], v[172:175], v[218:221], v[94:97]
	v_mfma_f32_16x16x32_bf16 v[90:93], v[176:179], v[214:217], v[90:93]
	v_mfma_f32_16x16x32_bf16 v[90:93], v[180:183], v[218:221], v[90:93]
	v_mfma_f32_16x16x32_bf16 v[70:73], v[168:171], v[222:225], v[70:73]
	v_mfma_f32_16x16x32_bf16 v[70:73], v[172:175], v[226:229], v[70:73]
	v_mfma_f32_16x16x32_bf16 v[66:69], v[176:179], v[222:225], v[66:69]
	v_mfma_f32_16x16x32_bf16 v[66:69], v[180:183], v[226:229], v[66:69]
	s_setprio 0
	s_barrier
	s_add_i32 s66, s67, s97
	v_lshl_add_u64 v[184:185], s[38:39], 0, v[156:157]
	s_mov_b32 m0, s66
	ds_read_b128 v[198:201], v197 offset:16384
	ds_read_b128 v[202:205], v197 offset:17408
	ds_read_b128 v[206:209], v197 offset:18432
	ds_read_b128 v[210:213], v197 offset:19456
	ds_read_b128 v[214:217], v197 offset:20480
	ds_read_b128 v[218:221], v197 offset:21504
	ds_read_b128 v[222:225], v197 offset:22528
	ds_read_b128 v[226:229], v197 offset:23552
	global_load_lds_dwordx4 v[184:185], off
	s_add_i32 m0, s66, 0x2000
	s_add_u32 s66, s38, 0x100000
	v_lshl_add_u64 v[230:231], s[38:39], 0, v[160:161]
	s_addc_u32 s67, s39, 0
	s_add_i32 vcc_hi, vcc_hi, s97
	global_load_lds_dwordx4 v[230:231], off
	v_lshl_add_u64 v[232:233], s[66:67], 0, v[156:157]
	s_mov_b32 m0, vcc_hi
	v_lshl_add_u64 v[234:235], s[86:87], 0, v[158:159]
	global_load_lds_dwordx4 v[232:233], off
	v_lshl_add_u64 v[232:233], s[66:67], 0, v[160:161]
	s_add_i32 m0, vcc_hi, 0x2000
	s_nop 0
	global_load_lds_dwordx4 v[232:233], off
	v_lshl_add_u64 v[232:233], s[86:87], 0, v[154:155]
	s_mov_b32 m0, s85
	s_nop 0
	global_load_lds_dwordx4 v[232:233], off
	s_mov_b32 m0, s92
	s_nop 0
	global_load_lds_dwordx4 v[234:235], off
	s_waitcnt vmcnt(8)
	s_waitcnt lgkmcnt(0)
	s_barrier
	s_setprio 1
	s_waitcnt lgkmcnt(0)
	v_mfma_f32_16x16x32_bf16 v[62:65], v[130:133], v[198:201], v[62:65]
	v_mfma_f32_16x16x32_bf16 v[62:65], v[134:137], v[202:205], v[62:65]
	v_mfma_f32_16x16x32_bf16 v[58:61], v[138:141], v[198:201], v[58:61]
	v_mfma_f32_16x16x32_bf16 v[58:61], v[142:145], v[202:205], v[58:61]
	v_mfma_f32_16x16x32_bf16 v[38:41], v[130:133], v[206:209], v[38:41]
	v_mfma_f32_16x16x32_bf16 v[38:41], v[134:137], v[210:213], v[38:41]
	v_mfma_f32_16x16x32_bf16 v[34:37], v[138:141], v[206:209], v[34:37]
	v_mfma_f32_16x16x32_bf16 v[34:37], v[142:145], v[210:213], v[34:37]
	v_mfma_f32_16x16x32_bf16 v[22:25], v[130:133], v[214:217], v[22:25]
	v_mfma_f32_16x16x32_bf16 v[22:25], v[134:137], v[218:221], v[22:25]
	v_mfma_f32_16x16x32_bf16 v[18:21], v[138:141], v[214:217], v[18:21]
	v_mfma_f32_16x16x32_bf16 v[18:21], v[142:145], v[218:221], v[18:21]
	v_mfma_f32_16x16x32_bf16 v[6:9], v[130:133], v[222:225], v[6:9]
	v_mfma_f32_16x16x32_bf16 v[6:9], v[134:137], v[226:229], v[6:9]
	v_mfma_f32_16x16x32_bf16 v[2:5], v[138:141], v[222:225], v[2:5]
	v_mfma_f32_16x16x32_bf16 v[2:5], v[142:145], v[226:229], v[2:5]
	s_setprio 0
	s_setprio 1
	v_mfma_f32_16x16x32_bf16 v[78:81], v[168:171], v[198:201], v[78:81]
	v_mfma_f32_16x16x32_bf16 v[78:81], v[172:175], v[202:205], v[78:81]
	v_mfma_f32_16x16x32_bf16 v[74:77], v[176:179], v[198:201], v[74:77]
	v_mfma_f32_16x16x32_bf16 v[74:77], v[180:183], v[202:205], v[74:77]
	v_mfma_f32_16x16x32_bf16 v[46:49], v[168:171], v[206:209], v[46:49]
	v_mfma_f32_16x16x32_bf16 v[46:49], v[172:175], v[210:213], v[46:49]
	v_mfma_f32_16x16x32_bf16 v[42:45], v[176:179], v[206:209], v[42:45]
	v_mfma_f32_16x16x32_bf16 v[42:45], v[180:183], v[210:213], v[42:45]
	v_mfma_f32_16x16x32_bf16 v[30:33], v[168:171], v[214:217], v[30:33]
	v_mfma_f32_16x16x32_bf16 v[30:33], v[172:175], v[218:221], v[30:33]
	v_mfma_f32_16x16x32_bf16 v[26:29], v[176:179], v[214:217], v[26:29]
	v_mfma_f32_16x16x32_bf16 v[26:29], v[180:183], v[218:221], v[26:29]
	v_mfma_f32_16x16x32_bf16 v[14:17], v[168:171], v[222:225], v[14:17]
	v_mfma_f32_16x16x32_bf16 v[14:17], v[172:175], v[226:229], v[14:17]
	v_mfma_f32_16x16x32_bf16 v[10:13], v[176:179], v[222:225], v[10:13]
	v_mfma_f32_16x16x32_bf16 v[10:13], v[180:183], v[226:229], v[10:13]
	s_setprio 0
	s_barrier
	s_add_i32 vcc_hi, 0, 0x18000
	s_add_i32 s56, 0, 0x1c000
	v_add_u32_e32 v142, vcc_hi, v1
	v_add_u32_e32 v180, s56, v1
	ds_read_b128 v[130:133], v142
	ds_read_b128 v[134:137], v142 offset:1024
	ds_read_b128 v[138:141], v142 offset:2048
	ds_read_b128 v[142:145], v142 offset:3072
	ds_read_b128 v[168:171], v180
	ds_read_b128 v[172:175], v180 offset:1024
	ds_read_b128 v[176:179], v180 offset:2048
	ds_read_b128 v[180:183], v180 offset:3072
	s_add_u32 s66, s86, 0x100000
	s_addc_u32 s67, s87, 0
	s_mov_b32 m0, s93
	v_lshl_add_u64 v[236:237], s[66:67], 0, v[154:155]
	ds_read_b128 v[198:201], v197 offset:32768
	ds_read_b128 v[202:205], v197 offset:33792
	ds_read_b128 v[206:209], v197 offset:34816
	ds_read_b128 v[210:213], v197 offset:35840
	ds_read_b128 v[214:217], v197 offset:36864
	ds_read_b128 v[218:221], v197 offset:37888
	ds_read_b128 v[222:225], v197 offset:38912
	ds_read_b128 v[226:229], v197 offset:39936
	global_load_lds_dwordx4 v[236:237], off
	v_lshl_add_u64 v[236:237], s[66:67], 0, v[158:159]
	s_mov_b32 m0, s42
	s_nop 0
	global_load_lds_dwordx4 v[236:237], off
	s_waitcnt vmcnt(8)
	s_waitcnt lgkmcnt(0)
	s_barrier
	s_setprio 1
	s_waitcnt lgkmcnt(0)
	v_mfma_f32_16x16x32_bf16 v[114:117], v[130:133], v[198:201], v[114:117]
	v_mfma_f32_16x16x32_bf16 v[114:117], v[134:137], v[202:205], v[114:117]
	v_mfma_f32_16x16x32_bf16 v[118:121], v[138:141], v[198:201], v[118:121]
	v_mfma_f32_16x16x32_bf16 v[118:121], v[142:145], v[202:205], v[118:121]
	v_mfma_f32_16x16x32_bf16 v[102:105], v[130:133], v[206:209], v[102:105]
	v_mfma_f32_16x16x32_bf16 v[102:105], v[134:137], v[210:213], v[102:105]
	v_mfma_f32_16x16x32_bf16 v[98:101], v[138:141], v[206:209], v[98:101]
	v_mfma_f32_16x16x32_bf16 v[98:101], v[142:145], v[210:213], v[98:101]
	v_mfma_f32_16x16x32_bf16 v[86:89], v[130:133], v[214:217], v[86:89]
	v_mfma_f32_16x16x32_bf16 v[86:89], v[134:137], v[218:221], v[86:89]
	v_mfma_f32_16x16x32_bf16 v[82:85], v[138:141], v[214:217], v[82:85]
	v_mfma_f32_16x16x32_bf16 v[82:85], v[142:145], v[218:221], v[82:85]
	v_mfma_f32_16x16x32_bf16 v[54:57], v[130:133], v[222:225], v[54:57]
	v_mfma_f32_16x16x32_bf16 v[54:57], v[134:137], v[226:229], v[54:57]
	v_mfma_f32_16x16x32_bf16 v[50:53], v[138:141], v[222:225], v[50:53]
	v_mfma_f32_16x16x32_bf16 v[50:53], v[142:145], v[226:229], v[50:53]
	s_setprio 0
	s_setprio 1
	v_mfma_f32_16x16x32_bf16 v[126:129], v[168:171], v[198:201], v[126:129]
	v_mfma_f32_16x16x32_bf16 v[126:129], v[172:175], v[202:205], v[126:129]
	v_mfma_f32_16x16x32_bf16 v[122:125], v[176:179], v[198:201], v[122:125]
	v_mfma_f32_16x16x32_bf16 v[122:125], v[180:183], v[202:205], v[122:125]
	v_mfma_f32_16x16x32_bf16 v[110:113], v[168:171], v[206:209], v[110:113]
	v_mfma_f32_16x16x32_bf16 v[110:113], v[172:175], v[210:213], v[110:113]
	v_mfma_f32_16x16x32_bf16 v[106:109], v[176:179], v[206:209], v[106:109]
	v_mfma_f32_16x16x32_bf16 v[106:109], v[180:183], v[210:213], v[106:109]
	v_mfma_f32_16x16x32_bf16 v[94:97], v[168:171], v[214:217], v[94:97]
	v_mfma_f32_16x16x32_bf16 v[94:97], v[172:175], v[218:221], v[94:97]
	v_mfma_f32_16x16x32_bf16 v[90:93], v[176:179], v[214:217], v[90:93]
	v_mfma_f32_16x16x32_bf16 v[90:93], v[180:183], v[218:221], v[90:93]
	v_mfma_f32_16x16x32_bf16 v[70:73], v[168:171], v[222:225], v[70:73]
	v_mfma_f32_16x16x32_bf16 v[70:73], v[172:175], v[226:229], v[70:73]
	v_mfma_f32_16x16x32_bf16 v[66:69], v[176:179], v[222:225], v[66:69]
	v_mfma_f32_16x16x32_bf16 v[66:69], v[180:183], v[226:229], v[66:69]
	s_setprio 0
	s_barrier
	s_add_i32 s57, vcc_hi, s97
	v_lshl_add_u64 v[184:185], v[184:185], 0, s[94:95]
	s_mov_b32 m0, s57
	ds_read_b128 v[198:201], v197 offset:49152
	ds_read_b128 v[202:205], v197 offset:50176
	ds_read_b128 v[206:209], v197 offset:51200
	ds_read_b128 v[210:213], v197 offset:52224
	ds_read_b128 v[214:217], v197 offset:53248
	ds_read_b128 v[218:221], v197 offset:54272
	ds_read_b128 v[222:225], v197 offset:55296
	ds_read_b128 v[226:229], v197 offset:56320
	global_load_lds_dwordx4 v[184:185], off
	s_add_i32 m0, s57, 0x2000
	s_add_u32 s38, s38, 0x100080
	v_lshl_add_u64 v[184:185], v[230:231], 0, s[94:95]
	s_addc_u32 s39, s39, 0
	s_add_i32 s56, s56, s97
	global_load_lds_dwordx4 v[184:185], off
	v_lshl_add_u64 v[184:185], s[38:39], 0, v[156:157]
	s_mov_b32 m0, s56
	s_nop 0
	global_load_lds_dwordx4 v[184:185], off
	v_lshl_add_u64 v[184:185], s[38:39], 0, v[160:161]
	s_add_i32 m0, s56, 0x2000
	s_nop 0
	global_load_lds_dwordx4 v[184:185], off
	v_lshl_add_u64 v[184:185], v[232:233], 0, s[94:95]
	s_mov_b32 m0, s43
	s_nop 0
	global_load_lds_dwordx4 v[184:185], off
	v_lshl_add_u64 v[184:185], v[234:235], 0, s[94:95]
	s_mov_b32 m0, s90
	s_nop 0
	global_load_lds_dwordx4 v[184:185], off
	s_waitcnt vmcnt(8)
	s_waitcnt lgkmcnt(0)
	s_barrier
	s_setprio 1
	s_waitcnt lgkmcnt(0)
	v_mfma_f32_16x16x32_bf16 v[62:65], v[130:133], v[198:201], v[62:65]
	v_mfma_f32_16x16x32_bf16 v[62:65], v[134:137], v[202:205], v[62:65]
	v_mfma_f32_16x16x32_bf16 v[58:61], v[138:141], v[198:201], v[58:61]
	v_mfma_f32_16x16x32_bf16 v[58:61], v[142:145], v[202:205], v[58:61]
	v_mfma_f32_16x16x32_bf16 v[38:41], v[130:133], v[206:209], v[38:41]
	v_mfma_f32_16x16x32_bf16 v[38:41], v[134:137], v[210:213], v[38:41]
	v_mfma_f32_16x16x32_bf16 v[34:37], v[138:141], v[206:209], v[34:37]
	v_mfma_f32_16x16x32_bf16 v[34:37], v[142:145], v[210:213], v[34:37]
	v_mfma_f32_16x16x32_bf16 v[22:25], v[130:133], v[214:217], v[22:25]
	v_mfma_f32_16x16x32_bf16 v[22:25], v[134:137], v[218:221], v[22:25]
	v_mfma_f32_16x16x32_bf16 v[18:21], v[138:141], v[214:217], v[18:21]
	v_mfma_f32_16x16x32_bf16 v[18:21], v[142:145], v[218:221], v[18:21]
	v_mfma_f32_16x16x32_bf16 v[6:9], v[130:133], v[222:225], v[6:9]
	v_mfma_f32_16x16x32_bf16 v[6:9], v[134:137], v[226:229], v[6:9]
	v_mfma_f32_16x16x32_bf16 v[2:5], v[138:141], v[222:225], v[2:5]
	v_mfma_f32_16x16x32_bf16 v[2:5], v[142:145], v[226:229], v[2:5]
	s_setprio 0
	s_setprio 1
	v_mfma_f32_16x16x32_bf16 v[78:81], v[168:171], v[198:201], v[78:81]
	v_mfma_f32_16x16x32_bf16 v[78:81], v[172:175], v[202:205], v[78:81]
	v_mfma_f32_16x16x32_bf16 v[74:77], v[176:179], v[198:201], v[74:77]
	v_mfma_f32_16x16x32_bf16 v[74:77], v[180:183], v[202:205], v[74:77]
	v_mfma_f32_16x16x32_bf16 v[46:49], v[168:171], v[206:209], v[46:49]
	v_mfma_f32_16x16x32_bf16 v[46:49], v[172:175], v[210:213], v[46:49]
	v_mfma_f32_16x16x32_bf16 v[42:45], v[176:179], v[206:209], v[42:45]
	v_mfma_f32_16x16x32_bf16 v[42:45], v[180:183], v[210:213], v[42:45]
	v_mfma_f32_16x16x32_bf16 v[30:33], v[168:171], v[214:217], v[30:33]
	v_mfma_f32_16x16x32_bf16 v[30:33], v[172:175], v[218:221], v[30:33]
	v_mfma_f32_16x16x32_bf16 v[26:29], v[176:179], v[214:217], v[26:29]
	v_mfma_f32_16x16x32_bf16 v[26:29], v[180:183], v[218:221], v[26:29]
	v_mfma_f32_16x16x32_bf16 v[14:17], v[168:171], v[222:225], v[14:17]
	v_mfma_f32_16x16x32_bf16 v[14:17], v[172:175], v[226:229], v[14:17]
	v_mfma_f32_16x16x32_bf16 v[10:13], v[176:179], v[222:225], v[10:13]
	v_mfma_f32_16x16x32_bf16 v[10:13], v[180:183], v[226:229], v[10:13]
	s_setprio 0
	s_barrier
	s_add_u32 s40, s40, 0x100
	s_addc_u32 s49, s49, 0
	s_add_u32 s10, s10, 0x100
	s_addc_u32 s11, s11, 0
	s_cmp_ge_u32 vcc_lo, s19
	s_mov_b32 s38, vcc_lo
	s_cbranch_scc0 .LBB0_262
	v_readlane_b32 s10, v254, 27
	v_readlane_b32 s11, v254, 28
	s_and_b64 vcc, exec, s[10:11]
	s_cbranch_vccz .LBB0_270
	s_barrier
	s_cmp_lt_i32 s18, 0
	s_mov_b64 s[10:11], -1
	s_cbranch_scc1 .LBB0_271

.LBB0_1693:
	ds_read_b128 v[128:131], v169
	ds_read_b128 v[132:135], v169 offset:1024
	ds_read_b128 v[136:139], v169 offset:2048
	ds_read_b128 v[140:143], v169 offset:3072
	ds_read_b128 v[158:161], v170
	ds_read_b128 v[162:165], v170 offset:1024
	ds_read_b128 v[172:175], v170 offset:2048
	ds_read_b128 v[176:179], v170 offset:3072
	s_add_u32 s24, s22, 0xfff80080
	s_addc_u32 s25, s23, -1
	s_cmp_eq_u32 s36, 4
	s_cselect_b32 s27, s5, s25
	s_cselect_b32 s26, s4, s24
	s_cselect_b32 s25, s13, s35
	s_cselect_b32 s24, s15, s34
	v_lshl_add_u64 v[212:213], s[22:23], 0, v[152:153]
	s_add_i32 m0, s94, 0xc000
	ds_read_b128 v[180:183], v171
	ds_read_b128 v[184:187], v171 offset:1024
	ds_read_b128 v[188:191], v171 offset:2048
	ds_read_b128 v[192:195], v171 offset:3072
	ds_read_b128 v[196:199], v171 offset:4096
	ds_read_b128 v[200:203], v171 offset:5120
	ds_read_b128 v[204:207], v171 offset:6144
	ds_read_b128 v[208:211], v171 offset:7168
	global_load_lds_dwordx4 v[212:213], off
	v_lshl_add_u64 v[212:213], s[22:23], 0, v[154:155]
	s_add_i32 m0, s94, 0xe000
	s_nop 0
	global_load_lds_dwordx4 v[212:213], off
	s_waitcnt vmcnt(8)
	s_waitcnt lgkmcnt(0)
	s_barrier
	s_setprio 1
	s_waitcnt lgkmcnt(0)
	v_mfma_f32_16x16x32_bf16 v[80:83], v[128:131], v[180:183], v[80:83]
	v_mfma_f32_16x16x32_bf16 v[80:83], v[132:135], v[184:187], v[80:83]
	v_mfma_f32_16x16x32_bf16 v[92:95], v[136:139], v[180:183], v[92:95]
	v_mfma_f32_16x16x32_bf16 v[92:95], v[140:143], v[184:187], v[92:95]
	v_mfma_f32_16x16x32_bf16 v[84:87], v[128:131], v[188:191], v[84:87]
	v_mfma_f32_16x16x32_bf16 v[84:87], v[132:135], v[192:195], v[84:87]
	v_mfma_f32_16x16x32_bf16 v[96:99], v[136:139], v[188:191], v[96:99]
	v_mfma_f32_16x16x32_bf16 v[96:99], v[140:143], v[192:195], v[96:99]
	v_mfma_f32_16x16x32_bf16 v[88:91], v[128:131], v[196:199], v[88:91]
	v_mfma_f32_16x16x32_bf16 v[88:91], v[132:135], v[200:203], v[88:91]
	v_mfma_f32_16x16x32_bf16 v[100:103], v[136:139], v[196:199], v[100:103]
	v_mfma_f32_16x16x32_bf16 v[100:103], v[140:143], v[200:203], v[100:103]
	v_mfma_f32_16x16x32_bf16 v[72:75], v[128:131], v[204:207], v[72:75]
	v_mfma_f32_16x16x32_bf16 v[72:75], v[132:135], v[208:211], v[72:75]
	v_mfma_f32_16x16x32_bf16 v[76:79], v[136:139], v[204:207], v[76:79]
	v_mfma_f32_16x16x32_bf16 v[76:79], v[140:143], v[208:211], v[76:79]
	s_setprio 0
	s_setprio 1
	v_mfma_f32_16x16x32_bf16 v[104:107], v[158:161], v[180:183], v[104:107]
	v_mfma_f32_16x16x32_bf16 v[104:107], v[162:165], v[184:187], v[104:107]
	v_mfma_f32_16x16x32_bf16 v[116:119], v[172:175], v[180:183], v[116:119]
	v_mfma_f32_16x16x32_bf16 v[116:119], v[176:179], v[184:187], v[116:119]
	v_mfma_f32_16x16x32_bf16 v[108:111], v[158:161], v[188:191], v[108:111]
	v_mfma_f32_16x16x32_bf16 v[108:111], v[162:165], v[192:195], v[108:111]
	v_mfma_f32_16x16x32_bf16 v[120:123], v[172:175], v[188:191], v[120:123]
	v_mfma_f32_16x16x32_bf16 v[120:123], v[176:179], v[192:195], v[120:123]
	v_mfma_f32_16x16x32_bf16 v[112:115], v[158:161], v[196:199], v[112:115]
	v_mfma_f32_16x16x32_bf16 v[112:115], v[162:165], v[200:203], v[112:115]
	v_mfma_f32_16x16x32_bf16 v[124:127], v[172:175], v[196:199], v[124:127]
	v_mfma_f32_16x16x32_bf16 v[124:127], v[176:179], v[200:203], v[124:127]
	v_mfma_f32_16x16x32_bf16 v[68:71], v[158:161], v[204:207], v[68:71]
	v_mfma_f32_16x16x32_bf16 v[68:71], v[162:165], v[208:211], v[68:71]
	v_mfma_f32_16x16x32_bf16 v[64:67], v[172:175], v[204:207], v[64:67]
	v_mfma_f32_16x16x32_bf16 v[64:67], v[176:179], v[208:211], v[64:67]
	s_setprio 0
	s_barrier
	s_add_i32 s37, s31, s97
	v_lshl_add_u64 v[212:213], s[24:25], 0, v[148:149]
	s_mov_b32 m0, s37
	ds_read_b128 v[180:183], v171 offset:16384
	ds_read_b128 v[184:187], v171 offset:17408
	ds_read_b128 v[188:191], v171 offset:18432
	ds_read_b128 v[192:195], v171 offset:19456
	ds_read_b128 v[196:199], v171 offset:20480
	ds_read_b128 v[200:203], v171 offset:21504
	ds_read_b128 v[204:207], v171 offset:22528
	ds_read_b128 v[208:211], v171 offset:23552
	global_load_lds_dwordx4 v[212:213], off
	s_add_i32 m0, s37, 0x2000
	s_add_u32 s38, s24, 0x20000
	v_lshl_add_u64 v[214:215], s[24:25], 0, v[144:145]
	s_addc_u32 s39, s25, 0
	s_add_i32 s37, s33, s97
	global_load_lds_dwordx4 v[214:215], off
	v_lshl_add_u64 v[216:217], s[38:39], 0, v[148:149]
	s_mov_b32 m0, s37
	v_lshl_add_u64 v[218:219], s[26:27], 0, v[146:147]
	global_load_lds_dwordx4 v[216:217], off
	v_lshl_add_u64 v[216:217], s[38:39], 0, v[144:145]
	s_add_i32 m0, s37, 0x2000
	s_nop 0
	global_load_lds_dwordx4 v[216:217], off
	v_lshl_add_u64 v[216:217], s[26:27], 0, v[150:151]
	s_mov_b32 m0, s94
	s_nop 0
	global_load_lds_dwordx4 v[216:217], off
	s_mov_b32 m0, s3
	s_nop 0
	global_load_lds_dwordx4 v[218:219], off
	s_waitcnt vmcnt(8)
	s_waitcnt lgkmcnt(0)
	s_barrier
	s_setprio 1
	s_waitcnt lgkmcnt(0)
	v_mfma_f32_16x16x32_bf16 v[48:51], v[128:131], v[180:183], v[48:51]
	v_mfma_f32_16x16x32_bf16 v[48:51], v[132:135], v[184:187], v[48:51]
	v_mfma_f32_16x16x32_bf16 v[52:55], v[136:139], v[180:183], v[52:55]
	v_mfma_f32_16x16x32_bf16 v[52:55], v[140:143], v[184:187], v[52:55]
	v_mfma_f32_16x16x32_bf16 v[32:35], v[128:131], v[188:191], v[32:35]
	v_mfma_f32_16x16x32_bf16 v[32:35], v[132:135], v[192:195], v[32:35]
	v_mfma_f32_16x16x32_bf16 v[36:39], v[136:139], v[188:191], v[36:39]
	v_mfma_f32_16x16x32_bf16 v[36:39], v[140:143], v[192:195], v[36:39]
	v_mfma_f32_16x16x32_bf16 v[16:19], v[128:131], v[196:199], v[16:19]
	v_mfma_f32_16x16x32_bf16 v[16:19], v[132:135], v[200:203], v[16:19]
	v_mfma_f32_16x16x32_bf16 v[20:23], v[136:139], v[196:199], v[20:23]
	v_mfma_f32_16x16x32_bf16 v[20:23], v[140:143], v[200:203], v[20:23]
	v_mfma_f32_16x16x32_bf16 v[0:3], v[128:131], v[204:207], v[0:3]
	v_mfma_f32_16x16x32_bf16 v[0:3], v[132:135], v[208:211], v[0:3]
	v_mfma_f32_16x16x32_bf16 v[4:7], v[136:139], v[204:207], v[4:7]
	v_mfma_f32_16x16x32_bf16 v[4:7], v[140:143], v[208:211], v[4:7]
	s_setprio 0
	s_setprio 1
	v_mfma_f32_16x16x32_bf16 v[56:59], v[158:161], v[180:183], v[56:59]
	v_mfma_f32_16x16x32_bf16 v[56:59], v[162:165], v[184:187], v[56:59]
	v_mfma_f32_16x16x32_bf16 v[60:63], v[172:175], v[180:183], v[60:63]
	v_mfma_f32_16x16x32_bf16 v[60:63], v[176:179], v[184:187], v[60:63]
	v_mfma_f32_16x16x32_bf16 v[40:43], v[158:161], v[188:191], v[40:43]
	v_mfma_f32_16x16x32_bf16 v[40:43], v[162:165], v[192:195], v[40:43]
	v_mfma_f32_16x16x32_bf16 v[44:47], v[172:175], v[188:191], v[44:47]
	v_mfma_f32_16x16x32_bf16 v[44:47], v[176:179], v[192:195], v[44:47]
	v_mfma_f32_16x16x32_bf16 v[24:27], v[158:161], v[196:199], v[24:27]
	v_mfma_f32_16x16x32_bf16 v[24:27], v[162:165], v[200:203], v[24:27]
	v_mfma_f32_16x16x32_bf16 v[28:31], v[172:175], v[196:199], v[28:31]
	v_mfma_f32_16x16x32_bf16 v[28:31], v[176:179], v[200:203], v[28:31]
	v_mfma_f32_16x16x32_bf16 v[8:11], v[158:161], v[204:207], v[8:11]
	v_mfma_f32_16x16x32_bf16 v[8:11], v[162:165], v[208:211], v[8:11]
	v_mfma_f32_16x16x32_bf16 v[12:15], v[172:175], v[204:207], v[12:15]
	v_mfma_f32_16x16x32_bf16 v[12:15], v[176:179], v[208:211], v[12:15]
	s_setprio 0
	s_barrier
	s_add_i32 s37, 0, 0x18000
	s_add_i32 s38, 0, 0x1c000
	v_add_u32_e32 v140, s37, v167
	v_add_u32_e32 v176, s38, v167
	ds_read_b128 v[128:131], v140
	ds_read_b128 v[132:135], v140 offset:1024
	ds_read_b128 v[136:139], v140 offset:2048
	ds_read_b128 v[140:143], v140 offset:3072
	ds_read_b128 v[158:161], v176
	ds_read_b128 v[162:165], v176 offset:1024
	ds_read_b128 v[172:175], v176 offset:2048
	ds_read_b128 v[176:179], v176 offset:3072
	s_add_u32 s26, s26, 0x80000
	s_addc_u32 s27, s27, 0
	s_mov_b32 m0, s7
	v_lshl_add_u64 v[220:221], s[26:27], 0, v[150:151]
	ds_read_b128 v[180:183], v171 offset:32768
	ds_read_b128 v[184:187], v171 offset:33792
	ds_read_b128 v[188:191], v171 offset:34816
	ds_read_b128 v[192:195], v171 offset:35840
	ds_read_b128 v[196:199], v171 offset:36864
	ds_read_b128 v[200:203], v171 offset:37888
	ds_read_b128 v[204:207], v171 offset:38912
	ds_read_b128 v[208:211], v171 offset:39936
	global_load_lds_dwordx4 v[220:221], off
	v_lshl_add_u64 v[220:221], s[26:27], 0, v[146:147]
	s_mov_b32 m0, s19
	s_nop 0
	global_load_lds_dwordx4 v[220:221], off
	s_waitcnt vmcnt(8)
	s_waitcnt lgkmcnt(0)
	s_barrier
	s_setprio 1
	s_waitcnt lgkmcnt(0)
	v_mfma_f32_16x16x32_bf16 v[80:83], v[128:131], v[180:183], v[80:83]
	v_mfma_f32_16x16x32_bf16 v[80:83], v[132:135], v[184:187], v[80:83]
	v_mfma_f32_16x16x32_bf16 v[92:95], v[136:139], v[180:183], v[92:95]
	v_mfma_f32_16x16x32_bf16 v[92:95], v[140:143], v[184:187], v[92:95]
	v_mfma_f32_16x16x32_bf16 v[84:87], v[128:131], v[188:191], v[84:87]
	v_mfma_f32_16x16x32_bf16 v[84:87], v[132:135], v[192:195], v[84:87]
	v_mfma_f32_16x16x32_bf16 v[96:99], v[136:139], v[188:191], v[96:99]
	v_mfma_f32_16x16x32_bf16 v[96:99], v[140:143], v[192:195], v[96:99]
	v_mfma_f32_16x16x32_bf16 v[88:91], v[128:131], v[196:199], v[88:91]
	v_mfma_f32_16x16x32_bf16 v[88:91], v[132:135], v[200:203], v[88:91]
	v_mfma_f32_16x16x32_bf16 v[100:103], v[136:139], v[196:199], v[100:103]
	v_mfma_f32_16x16x32_bf16 v[100:103], v[140:143], v[200:203], v[100:103]
	v_mfma_f32_16x16x32_bf16 v[72:75], v[128:131], v[204:207], v[72:75]
	v_mfma_f32_16x16x32_bf16 v[72:75], v[132:135], v[208:211], v[72:75]
	v_mfma_f32_16x16x32_bf16 v[76:79], v[136:139], v[204:207], v[76:79]
	v_mfma_f32_16x16x32_bf16 v[76:79], v[140:143], v[208:211], v[76:79]
	s_setprio 0
	s_setprio 1
	v_mfma_f32_16x16x32_bf16 v[104:107], v[158:161], v[180:183], v[104:107]
	v_mfma_f32_16x16x32_bf16 v[104:107], v[162:165], v[184:187], v[104:107]
	v_mfma_f32_16x16x32_bf16 v[116:119], v[172:175], v[180:183], v[116:119]
	v_mfma_f32_16x16x32_bf16 v[116:119], v[176:179], v[184:187], v[116:119]
	v_mfma_f32_16x16x32_bf16 v[108:111], v[158:161], v[188:191], v[108:111]
	v_mfma_f32_16x16x32_bf16 v[108:111], v[162:165], v[192:195], v[108:111]
	v_mfma_f32_16x16x32_bf16 v[120:123], v[172:175], v[188:191], v[120:123]
	v_mfma_f32_16x16x32_bf16 v[120:123], v[176:179], v[192:195], v[120:123]
	v_mfma_f32_16x16x32_bf16 v[112:115], v[158:161], v[196:199], v[112:115]
	v_mfma_f32_16x16x32_bf16 v[112:115], v[162:165], v[200:203], v[112:115]
	v_mfma_f32_16x16x32_bf16 v[124:127], v[172:175], v[196:199], v[124:127]
	v_mfma_f32_16x16x32_bf16 v[124:127], v[176:179], v[200:203], v[124:127]
	v_mfma_f32_16x16x32_bf16 v[68:71], v[158:161], v[204:207], v[68:71]
	v_mfma_f32_16x16x32_bf16 v[68:71], v[162:165], v[208:211], v[68:71]
	v_mfma_f32_16x16x32_bf16 v[64:67], v[172:175], v[204:207], v[64:67]
	v_mfma_f32_16x16x32_bf16 v[64:67], v[176:179], v[208:211], v[64:67]
	s_setprio 0
	s_barrier
	s_add_i32 s26, s37, s97
	v_lshl_add_u64 v[212:213], v[212:213], 0, s[0:1]
	s_mov_b32 m0, s26
	ds_read_b128 v[180:183], v171 offset:49152
	ds_read_b128 v[184:187], v171 offset:50176
	ds_read_b128 v[188:191], v171 offset:51200
	ds_read_b128 v[192:195], v171 offset:52224
	ds_read_b128 v[196:199], v171 offset:53248
	ds_read_b128 v[200:203], v171 offset:54272
	ds_read_b128 v[204:207], v171 offset:55296
	ds_read_b128 v[208:211], v171 offset:56320
	global_load_lds_dwordx4 v[212:213], off
	s_add_i32 m0, s26, 0x2000
	s_add_u32 s24, s24, 0x20080
	v_lshl_add_u64 v[212:213], v[214:215], 0, s[0:1]
	s_addc_u32 s25, s25, 0
	s_add_i32 s26, s38, s97
	global_load_lds_dwordx4 v[212:213], off
	v_lshl_add_u64 v[212:213], s[24:25], 0, v[148:149]
	s_mov_b32 m0, s26
	s_nop 0
	global_load_lds_dwordx4 v[212:213], off
	v_lshl_add_u64 v[212:213], s[24:25], 0, v[144:145]
	s_add_i32 m0, s26, 0x2000
	s_nop 0
	global_load_lds_dwordx4 v[212:213], off
	v_lshl_add_u64 v[212:213], v[216:217], 0, s[0:1]
	s_mov_b32 m0, s28
	s_nop 0
	global_load_lds_dwordx4 v[212:213], off
	v_lshl_add_u64 v[212:213], v[218:219], 0, s[0:1]
	s_mov_b32 m0, s29
	s_nop 0
	global_load_lds_dwordx4 v[212:213], off
	s_waitcnt vmcnt(8)
	s_waitcnt lgkmcnt(0)
	s_barrier
	s_setprio 1
	s_waitcnt lgkmcnt(0)
	v_mfma_f32_16x16x32_bf16 v[48:51], v[128:131], v[180:183], v[48:51]
	v_mfma_f32_16x16x32_bf16 v[48:51], v[132:135], v[184:187], v[48:51]
	v_mfma_f32_16x16x32_bf16 v[52:55], v[136:139], v[180:183], v[52:55]
	v_mfma_f32_16x16x32_bf16 v[52:55], v[140:143], v[184:187], v[52:55]
	v_mfma_f32_16x16x32_bf16 v[32:35], v[128:131], v[188:191], v[32:35]
	v_mfma_f32_16x16x32_bf16 v[32:35], v[132:135], v[192:195], v[32:35]
	v_mfma_f32_16x16x32_bf16 v[36:39], v[136:139], v[188:191], v[36:39]
	v_mfma_f32_16x16x32_bf16 v[36:39], v[140:143], v[192:195], v[36:39]
	v_mfma_f32_16x16x32_bf16 v[16:19], v[128:131], v[196:199], v[16:19]
	v_mfma_f32_16x16x32_bf16 v[16:19], v[132:135], v[200:203], v[16:19]
	v_mfma_f32_16x16x32_bf16 v[20:23], v[136:139], v[196:199], v[20:23]
	v_mfma_f32_16x16x32_bf16 v[20:23], v[140:143], v[200:203], v[20:23]
	v_mfma_f32_16x16x32_bf16 v[0:3], v[128:131], v[204:207], v[0:3]
	v_mfma_f32_16x16x32_bf16 v[0:3], v[132:135], v[208:211], v[0:3]
	v_mfma_f32_16x16x32_bf16 v[4:7], v[136:139], v[204:207], v[4:7]
	v_mfma_f32_16x16x32_bf16 v[4:7], v[140:143], v[208:211], v[4:7]
	s_setprio 0
	s_setprio 1
	v_mfma_f32_16x16x32_bf16 v[56:59], v[158:161], v[180:183], v[56:59]
	v_mfma_f32_16x16x32_bf16 v[56:59], v[162:165], v[184:187], v[56:59]
	v_mfma_f32_16x16x32_bf16 v[60:63], v[172:175], v[180:183], v[60:63]
	v_mfma_f32_16x16x32_bf16 v[60:63], v[176:179], v[184:187], v[60:63]
	v_mfma_f32_16x16x32_bf16 v[40:43], v[158:161], v[188:191], v[40:43]
	v_mfma_f32_16x16x32_bf16 v[40:43], v[162:165], v[192:195], v[40:43]
	v_mfma_f32_16x16x32_bf16 v[44:47], v[172:175], v[188:191], v[44:47]
	v_mfma_f32_16x16x32_bf16 v[44:47], v[176:179], v[192:195], v[44:47]
	v_mfma_f32_16x16x32_bf16 v[24:27], v[158:161], v[196:199], v[24:27]
	v_mfma_f32_16x16x32_bf16 v[24:27], v[162:165], v[200:203], v[24:27]
	v_mfma_f32_16x16x32_bf16 v[28:31], v[172:175], v[196:199], v[28:31]
	v_mfma_f32_16x16x32_bf16 v[28:31], v[176:179], v[200:203], v[28:31]
	v_mfma_f32_16x16x32_bf16 v[8:11], v[158:161], v[204:207], v[8:11]
	v_mfma_f32_16x16x32_bf16 v[8:11], v[162:165], v[208:211], v[8:11]
	v_mfma_f32_16x16x32_bf16 v[12:15], v[172:175], v[204:207], v[12:15]
	v_mfma_f32_16x16x32_bf16 v[12:15], v[176:179], v[208:211], v[12:15]
	s_setprio 0
	s_barrier
	s_add_i32 s36, s36, 2
	s_add_u32 s34, s34, 0x100
	s_addc_u32 s35, s35, 0
	s_add_u32 s22, s22, 0x100
	s_addc_u32 s23, s23, 0
	s_cmp_gt_u32 s36, 5
	s_cbranch_scc0 .LBB0_1693
	v_readlane_b32 s22, v254, 27
	v_readlane_b32 s23, v254, 28
	s_and_b64 vcc, exec, s[22:23]
	s_cbranch_vccz .LBB0_1696
	s_barrier

.LBB0_2020:
	ds_read_b128 v[128:131], v244
	ds_read_b128 v[132:135], v244 offset:1024
	ds_read_b128 v[136:139], v244 offset:2048
	ds_read_b128 v[140:143], v244 offset:3072
	ds_read_b128 v[144:147], v245
	ds_read_b128 v[148:151], v245 offset:1024
	ds_read_b128 v[152:155], v245 offset:2048
	ds_read_b128 v[156:159], v245 offset:3072
	s_add_i32 s71, s46, 2
	s_add_u32 s47, s44, 0xfff00080
	s_addc_u32 s48, s45, -1
	s_cmp_eq_u32 s68, s46
	s_cselect_b32 s46, s43, s69
	s_cselect_b32 s49, s5, s48
	s_cselect_b32 s48, s23, s47
	s_cselect_b32 s47, s21, s70
	v_lshl_add_u64 v[192:193], s[44:45], 0, v[218:219]
	s_add_i32 m0, s94, 0xc000
	ds_read_b128 v[160:163], v246
	ds_read_b128 v[164:167], v246 offset:1024
	ds_read_b128 v[168:171], v246 offset:2048
	ds_read_b128 v[172:175], v246 offset:3072
	ds_read_b128 v[176:179], v246 offset:4096
	ds_read_b128 v[180:183], v246 offset:5120
	ds_read_b128 v[184:187], v246 offset:6144
	ds_read_b128 v[188:191], v246 offset:7168
	global_load_lds_dwordx4 v[192:193], off
	v_lshl_add_u64 v[192:193], s[44:45], 0, v[220:221]
	s_add_i32 m0, s94, 0xe000
	s_nop 0
	global_load_lds_dwordx4 v[192:193], off
	s_waitcnt vmcnt(8)
	s_waitcnt lgkmcnt(0)
	s_barrier
	s_setprio 1
	s_waitcnt lgkmcnt(0)
	v_mfma_f32_16x16x32_bf16 v[112:115], v[128:131], v[160:163], v[112:115]
	v_mfma_f32_16x16x32_bf16 v[112:115], v[132:135], v[164:167], v[112:115]
	v_mfma_f32_16x16x32_bf16 v[116:119], v[136:139], v[160:163], v[116:119]
	v_mfma_f32_16x16x32_bf16 v[116:119], v[140:143], v[164:167], v[116:119]
	v_mfma_f32_16x16x32_bf16 v[100:103], v[128:131], v[168:171], v[100:103]
	v_mfma_f32_16x16x32_bf16 v[100:103], v[132:135], v[172:175], v[100:103]
	v_mfma_f32_16x16x32_bf16 v[96:99], v[136:139], v[168:171], v[96:99]
	v_mfma_f32_16x16x32_bf16 v[96:99], v[140:143], v[172:175], v[96:99]
	v_mfma_f32_16x16x32_bf16 v[84:87], v[128:131], v[176:179], v[84:87]
	v_mfma_f32_16x16x32_bf16 v[84:87], v[132:135], v[180:183], v[84:87]
	v_mfma_f32_16x16x32_bf16 v[80:83], v[136:139], v[176:179], v[80:83]
	v_mfma_f32_16x16x32_bf16 v[80:83], v[140:143], v[180:183], v[80:83]
	v_mfma_f32_16x16x32_bf16 v[52:55], v[128:131], v[184:187], v[52:55]
	v_mfma_f32_16x16x32_bf16 v[52:55], v[132:135], v[188:191], v[52:55]
	v_mfma_f32_16x16x32_bf16 v[48:51], v[136:139], v[184:187], v[48:51]
	v_mfma_f32_16x16x32_bf16 v[48:51], v[140:143], v[188:191], v[48:51]
	s_setprio 0
	s_setprio 1
	v_mfma_f32_16x16x32_bf16 v[124:127], v[144:147], v[160:163], v[124:127]
	v_mfma_f32_16x16x32_bf16 v[124:127], v[148:151], v[164:167], v[124:127]
	v_mfma_f32_16x16x32_bf16 v[120:123], v[152:155], v[160:163], v[120:123]
	v_mfma_f32_16x16x32_bf16 v[120:123], v[156:159], v[164:167], v[120:123]
	v_mfma_f32_16x16x32_bf16 v[108:111], v[144:147], v[168:171], v[108:111]
	v_mfma_f32_16x16x32_bf16 v[108:111], v[148:151], v[172:175], v[108:111]
	v_mfma_f32_16x16x32_bf16 v[104:107], v[152:155], v[168:171], v[104:107]
	v_mfma_f32_16x16x32_bf16 v[104:107], v[156:159], v[172:175], v[104:107]
	v_mfma_f32_16x16x32_bf16 v[92:95], v[144:147], v[176:179], v[92:95]
	v_mfma_f32_16x16x32_bf16 v[92:95], v[148:151], v[180:183], v[92:95]
	v_mfma_f32_16x16x32_bf16 v[88:91], v[152:155], v[176:179], v[88:91]
	v_mfma_f32_16x16x32_bf16 v[88:91], v[156:159], v[180:183], v[88:91]
	v_mfma_f32_16x16x32_bf16 v[68:71], v[144:147], v[184:187], v[68:71]
	v_mfma_f32_16x16x32_bf16 v[68:71], v[148:151], v[188:191], v[68:71]
	v_mfma_f32_16x16x32_bf16 v[64:67], v[152:155], v[184:187], v[64:67]
	v_mfma_f32_16x16x32_bf16 v[64:67], v[156:159], v[188:191], v[64:67]
	s_setprio 0
	s_barrier
	s_add_i32 s76, s60, s97
	v_lshl_add_u64 v[192:193], s[46:47], 0, v[210:211]
	s_mov_b32 m0, s76
	ds_read_b128 v[160:163], v246 offset:16384
	ds_read_b128 v[164:167], v246 offset:17408
	ds_read_b128 v[168:171], v246 offset:18432
	ds_read_b128 v[172:175], v246 offset:19456
	ds_read_b128 v[176:179], v246 offset:20480
	ds_read_b128 v[180:183], v246 offset:21504
	ds_read_b128 v[184:187], v246 offset:22528
	ds_read_b128 v[188:191], v246 offset:23552
	global_load_lds_dwordx4 v[192:193], off
	s_add_i32 m0, s76, 0x2000
	s_add_u32 s76, s46, 0x100000
	v_lshl_add_u64 v[194:195], s[46:47], 0, v[214:215]
	s_addc_u32 s77, s47, 0
	s_add_i32 s78, s61, s97
	global_load_lds_dwordx4 v[194:195], off
	v_lshl_add_u64 v[196:197], s[76:77], 0, v[210:211]
	s_mov_b32 m0, s78
	v_lshl_add_u64 v[198:199], s[48:49], 0, v[212:213]
	global_load_lds_dwordx4 v[196:197], off
	v_lshl_add_u64 v[196:197], s[76:77], 0, v[214:215]
	s_add_i32 m0, s78, 0x2000
	s_nop 0
	global_load_lds_dwordx4 v[196:197], off
	v_lshl_add_u64 v[196:197], s[48:49], 0, v[208:209]
	s_mov_b32 m0, s94
	s_nop 0
	global_load_lds_dwordx4 v[196:197], off
	s_mov_b32 m0, s2
	s_nop 0
	global_load_lds_dwordx4 v[198:199], off
	s_waitcnt vmcnt(8)
	s_waitcnt lgkmcnt(0)
	s_barrier
	s_setprio 1
	s_waitcnt lgkmcnt(0)
	v_mfma_f32_16x16x32_bf16 v[60:63], v[128:131], v[160:163], v[60:63]
	v_mfma_f32_16x16x32_bf16 v[60:63], v[132:135], v[164:167], v[60:63]
	v_mfma_f32_16x16x32_bf16 v[56:59], v[136:139], v[160:163], v[56:59]
	v_mfma_f32_16x16x32_bf16 v[56:59], v[140:143], v[164:167], v[56:59]
	v_mfma_f32_16x16x32_bf16 v[36:39], v[128:131], v[168:171], v[36:39]
	v_mfma_f32_16x16x32_bf16 v[36:39], v[132:135], v[172:175], v[36:39]
	v_mfma_f32_16x16x32_bf16 v[32:35], v[136:139], v[168:171], v[32:35]
	v_mfma_f32_16x16x32_bf16 v[32:35], v[140:143], v[172:175], v[32:35]
	v_mfma_f32_16x16x32_bf16 v[20:23], v[128:131], v[176:179], v[20:23]
	v_mfma_f32_16x16x32_bf16 v[20:23], v[132:135], v[180:183], v[20:23]
	v_mfma_f32_16x16x32_bf16 v[16:19], v[136:139], v[176:179], v[16:19]
	v_mfma_f32_16x16x32_bf16 v[16:19], v[140:143], v[180:183], v[16:19]
	v_mfma_f32_16x16x32_bf16 v[4:7], v[128:131], v[184:187], v[4:7]
	v_mfma_f32_16x16x32_bf16 v[4:7], v[132:135], v[188:191], v[4:7]
	v_mfma_f32_16x16x32_bf16 v[0:3], v[136:139], v[184:187], v[0:3]
	v_mfma_f32_16x16x32_bf16 v[0:3], v[140:143], v[188:191], v[0:3]
	s_setprio 0
	s_setprio 1
	v_mfma_f32_16x16x32_bf16 v[76:79], v[144:147], v[160:163], v[76:79]
	v_mfma_f32_16x16x32_bf16 v[76:79], v[148:151], v[164:167], v[76:79]
	v_mfma_f32_16x16x32_bf16 v[72:75], v[152:155], v[160:163], v[72:75]
	v_mfma_f32_16x16x32_bf16 v[72:75], v[156:159], v[164:167], v[72:75]
	v_mfma_f32_16x16x32_bf16 v[44:47], v[144:147], v[168:171], v[44:47]
	v_mfma_f32_16x16x32_bf16 v[44:47], v[148:151], v[172:175], v[44:47]
	v_mfma_f32_16x16x32_bf16 v[40:43], v[152:155], v[168:171], v[40:43]
	v_mfma_f32_16x16x32_bf16 v[40:43], v[156:159], v[172:175], v[40:43]
	v_mfma_f32_16x16x32_bf16 v[28:31], v[144:147], v[176:179], v[28:31]
	v_mfma_f32_16x16x32_bf16 v[28:31], v[148:151], v[180:183], v[28:31]
	v_mfma_f32_16x16x32_bf16 v[24:27], v[152:155], v[176:179], v[24:27]
	v_mfma_f32_16x16x32_bf16 v[24:27], v[156:159], v[180:183], v[24:27]
	v_mfma_f32_16x16x32_bf16 v[12:15], v[144:147], v[184:187], v[12:15]
	v_mfma_f32_16x16x32_bf16 v[12:15], v[148:151], v[188:191], v[12:15]
	v_mfma_f32_16x16x32_bf16 v[8:11], v[152:155], v[184:187], v[8:11]
	v_mfma_f32_16x16x32_bf16 v[8:11], v[156:159], v[188:191], v[8:11]
	s_setprio 0
	s_barrier
	s_add_i32 s76, 0, 0x18000
	s_add_i32 s77, 0, 0x1c000
	v_add_u32_e32 v140, s76, v243
	v_add_u32_e32 v156, s77, v243
	ds_read_b128 v[128:131], v140
	ds_read_b128 v[132:135], v140 offset:1024
	ds_read_b128 v[136:139], v140 offset:2048
	ds_read_b128 v[140:143], v140 offset:3072
	ds_read_b128 v[144:147], v156
	ds_read_b128 v[148:151], v156 offset:1024
	ds_read_b128 v[152:155], v156 offset:2048
	ds_read_b128 v[156:159], v156 offset:3072
	s_add_u32 s48, s48, 0x100000
	s_addc_u32 s49, s49, 0
	s_mov_b32 m0, s3
	v_lshl_add_u64 v[200:201], s[48:49], 0, v[208:209]
	ds_read_b128 v[160:163], v246 offset:32768
	ds_read_b128 v[164:167], v246 offset:33792
	ds_read_b128 v[168:171], v246 offset:34816
	ds_read_b128 v[172:175], v246 offset:35840
	ds_read_b128 v[176:179], v246 offset:36864
	ds_read_b128 v[180:183], v246 offset:37888
	ds_read_b128 v[184:187], v246 offset:38912
	ds_read_b128 v[188:191], v246 offset:39936
	global_load_lds_dwordx4 v[200:201], off
	v_lshl_add_u64 v[200:201], s[48:49], 0, v[212:213]
	s_mov_b32 m0, s33
	s_nop 0
	global_load_lds_dwordx4 v[200:201], off
	s_waitcnt vmcnt(8)
	s_waitcnt lgkmcnt(0)
	s_barrier
	s_setprio 1
	s_waitcnt lgkmcnt(0)
	v_mfma_f32_16x16x32_bf16 v[112:115], v[128:131], v[160:163], v[112:115]
	v_mfma_f32_16x16x32_bf16 v[112:115], v[132:135], v[164:167], v[112:115]
	v_mfma_f32_16x16x32_bf16 v[116:119], v[136:139], v[160:163], v[116:119]
	v_mfma_f32_16x16x32_bf16 v[116:119], v[140:143], v[164:167], v[116:119]
	v_mfma_f32_16x16x32_bf16 v[100:103], v[128:131], v[168:171], v[100:103]
	v_mfma_f32_16x16x32_bf16 v[100:103], v[132:135], v[172:175], v[100:103]
	v_mfma_f32_16x16x32_bf16 v[96:99], v[136:139], v[168:171], v[96:99]
	v_mfma_f32_16x16x32_bf16 v[96:99], v[140:143], v[172:175], v[96:99]
	v_mfma_f32_16x16x32_bf16 v[84:87], v[128:131], v[176:179], v[84:87]
	v_mfma_f32_16x16x32_bf16 v[84:87], v[132:135], v[180:183], v[84:87]
	v_mfma_f32_16x16x32_bf16 v[80:83], v[136:139], v[176:179], v[80:83]
	v_mfma_f32_16x16x32_bf16 v[80:83], v[140:143], v[180:183], v[80:83]
	v_mfma_f32_16x16x32_bf16 v[52:55], v[128:131], v[184:187], v[52:55]
	v_mfma_f32_16x16x32_bf16 v[52:55], v[132:135], v[188:191], v[52:55]
	v_mfma_f32_16x16x32_bf16 v[48:51], v[136:139], v[184:187], v[48:51]
	v_mfma_f32_16x16x32_bf16 v[48:51], v[140:143], v[188:191], v[48:51]
	s_setprio 0
	s_setprio 1
	v_mfma_f32_16x16x32_bf16 v[124:127], v[144:147], v[160:163], v[124:127]
	v_mfma_f32_16x16x32_bf16 v[124:127], v[148:151], v[164:167], v[124:127]
	v_mfma_f32_16x16x32_bf16 v[120:123], v[152:155], v[160:163], v[120:123]
	v_mfma_f32_16x16x32_bf16 v[120:123], v[156:159], v[164:167], v[120:123]
	v_mfma_f32_16x16x32_bf16 v[108:111], v[144:147], v[168:171], v[108:111]
	v_mfma_f32_16x16x32_bf16 v[108:111], v[148:151], v[172:175], v[108:111]
	v_mfma_f32_16x16x32_bf16 v[104:107], v[152:155], v[168:171], v[104:107]
	v_mfma_f32_16x16x32_bf16 v[104:107], v[156:159], v[172:175], v[104:107]
	v_mfma_f32_16x16x32_bf16 v[92:95], v[144:147], v[176:179], v[92:95]
	v_mfma_f32_16x16x32_bf16 v[92:95], v[148:151], v[180:183], v[92:95]
	v_mfma_f32_16x16x32_bf16 v[88:91], v[152:155], v[176:179], v[88:91]
	v_mfma_f32_16x16x32_bf16 v[88:91], v[156:159], v[180:183], v[88:91]
	v_mfma_f32_16x16x32_bf16 v[68:71], v[144:147], v[184:187], v[68:71]
	v_mfma_f32_16x16x32_bf16 v[68:71], v[148:151], v[188:191], v[68:71]
	v_mfma_f32_16x16x32_bf16 v[64:67], v[152:155], v[184:187], v[64:67]
	v_mfma_f32_16x16x32_bf16 v[64:67], v[156:159], v[188:191], v[64:67]
	s_setprio 0
	s_barrier
	s_add_i32 s48, s76, s97
	v_lshl_add_u64 v[192:193], v[192:193], 0, s[16:17]
	s_mov_b32 m0, s48
	ds_read_b128 v[160:163], v246 offset:49152
	ds_read_b128 v[164:167], v246 offset:50176
	ds_read_b128 v[168:171], v246 offset:51200
	ds_read_b128 v[172:175], v246 offset:52224
	ds_read_b128 v[176:179], v246 offset:53248
	ds_read_b128 v[180:183], v246 offset:54272
	ds_read_b128 v[184:187], v246 offset:55296
	ds_read_b128 v[188:191], v246 offset:56320
	global_load_lds_dwordx4 v[192:193], off
	s_add_i32 m0, s48, 0x2000
	s_add_u32 s46, s46, 0x100080
	v_lshl_add_u64 v[192:193], v[194:195], 0, s[16:17]
	s_addc_u32 s47, s47, 0
	s_add_i32 s48, s77, s97
	global_load_lds_dwordx4 v[192:193], off
	v_lshl_add_u64 v[192:193], s[46:47], 0, v[210:211]
	s_mov_b32 m0, s48
	s_nop 0
	global_load_lds_dwordx4 v[192:193], off
	v_lshl_add_u64 v[192:193], s[46:47], 0, v[214:215]
	s_add_i32 m0, s48, 0x2000
	s_nop 0
	global_load_lds_dwordx4 v[192:193], off
	v_lshl_add_u64 v[192:193], v[196:197], 0, s[16:17]
	s_mov_b32 m0, s54
	s_nop 0
	global_load_lds_dwordx4 v[192:193], off
	v_lshl_add_u64 v[192:193], v[198:199], 0, s[16:17]
	s_mov_b32 m0, s55
	s_nop 0
	global_load_lds_dwordx4 v[192:193], off
	s_waitcnt vmcnt(8)
	s_waitcnt lgkmcnt(0)
	s_barrier
	s_setprio 1
	s_waitcnt lgkmcnt(0)
	v_mfma_f32_16x16x32_bf16 v[60:63], v[128:131], v[160:163], v[60:63]
	v_mfma_f32_16x16x32_bf16 v[60:63], v[132:135], v[164:167], v[60:63]
	v_mfma_f32_16x16x32_bf16 v[56:59], v[136:139], v[160:163], v[56:59]
	v_mfma_f32_16x16x32_bf16 v[56:59], v[140:143], v[164:167], v[56:59]
	v_mfma_f32_16x16x32_bf16 v[36:39], v[128:131], v[168:171], v[36:39]
	v_mfma_f32_16x16x32_bf16 v[36:39], v[132:135], v[172:175], v[36:39]
	v_mfma_f32_16x16x32_bf16 v[32:35], v[136:139], v[168:171], v[32:35]
	v_mfma_f32_16x16x32_bf16 v[32:35], v[140:143], v[172:175], v[32:35]
	v_mfma_f32_16x16x32_bf16 v[20:23], v[128:131], v[176:179], v[20:23]
	v_mfma_f32_16x16x32_bf16 v[20:23], v[132:135], v[180:183], v[20:23]
	v_mfma_f32_16x16x32_bf16 v[16:19], v[136:139], v[176:179], v[16:19]
	v_mfma_f32_16x16x32_bf16 v[16:19], v[140:143], v[180:183], v[16:19]
	v_mfma_f32_16x16x32_bf16 v[4:7], v[128:131], v[184:187], v[4:7]
	v_mfma_f32_16x16x32_bf16 v[4:7], v[132:135], v[188:191], v[4:7]
	v_mfma_f32_16x16x32_bf16 v[0:3], v[136:139], v[184:187], v[0:3]
	v_mfma_f32_16x16x32_bf16 v[0:3], v[140:143], v[188:191], v[0:3]
	s_setprio 0
	s_setprio 1
	v_mfma_f32_16x16x32_bf16 v[76:79], v[144:147], v[160:163], v[76:79]
	v_mfma_f32_16x16x32_bf16 v[76:79], v[148:151], v[164:167], v[76:79]
	v_mfma_f32_16x16x32_bf16 v[72:75], v[152:155], v[160:163], v[72:75]
	v_mfma_f32_16x16x32_bf16 v[72:75], v[156:159], v[164:167], v[72:75]
	v_mfma_f32_16x16x32_bf16 v[44:47], v[144:147], v[168:171], v[44:47]
	v_mfma_f32_16x16x32_bf16 v[44:47], v[148:151], v[172:175], v[44:47]
	v_mfma_f32_16x16x32_bf16 v[40:43], v[152:155], v[168:171], v[40:43]
	v_mfma_f32_16x16x32_bf16 v[40:43], v[156:159], v[172:175], v[40:43]
	v_mfma_f32_16x16x32_bf16 v[28:31], v[144:147], v[176:179], v[28:31]
	v_mfma_f32_16x16x32_bf16 v[28:31], v[148:151], v[180:183], v[28:31]
	v_mfma_f32_16x16x32_bf16 v[24:27], v[152:155], v[176:179], v[24:27]
	v_mfma_f32_16x16x32_bf16 v[24:27], v[156:159], v[180:183], v[24:27]
	v_mfma_f32_16x16x32_bf16 v[12:15], v[144:147], v[184:187], v[12:15]
	v_mfma_f32_16x16x32_bf16 v[12:15], v[148:151], v[188:191], v[12:15]
	v_mfma_f32_16x16x32_bf16 v[8:11], v[152:155], v[184:187], v[8:11]
	v_mfma_f32_16x16x32_bf16 v[8:11], v[156:159], v[188:191], v[8:11]
	s_setprio 0
	s_barrier
	s_add_u32 s69, s69, 0x100
	s_addc_u32 s70, s70, 0
	s_add_u32 s44, s44, 0x100
	s_addc_u32 s45, s45, 0
	s_cmp_ge_u32 s71, s67
	s_mov_b32 s46, s71
	s_cbranch_scc0 .LBB0_2020
	v_readlane_b32 s44, v254, 27
	v_readlane_b32 s45, v254, 28
	s_and_b64 vcc, exec, s[44:45]
	s_cbranch_vccz .LBB0_2028
	s_barrier
	s_cmp_lt_i32 s14, 0
	s_mov_b64 s[44:45], -1
	s_cbranch_scc1 .LBB0_2029

.LBB0_2289:
	ds_read_b128 v[148:151], v159
	ds_read_b128 v[164:167], v159 offset:1024
	ds_read_b128 v[168:171], v159 offset:2048
	ds_read_b128 v[172:175], v159 offset:3072
	ds_read_b128 v[176:179], v160
	ds_read_b128 v[180:183], v160 offset:1024
	ds_read_b128 v[184:187], v160 offset:2048
	ds_read_b128 v[188:191], v160 offset:3072
	s_add_i32 s87, s46, 2
	s_add_u32 s47, s44, 0xfff00080
	s_addc_u32 s48, s45, -1
	s_cmp_eq_u32 s43, s46
	s_cselect_b32 s46, s25, s85
	s_cselect_b32 s49, s37, s48
	s_cselect_b32 s48, s36, s47
	s_cselect_b32 s47, s5, s86
	v_lshl_add_u64 v[152:153], s[44:45], 0, v[142:143]
	s_add_i32 m0, s94, 0xc000
	ds_read_b128 v[192:195], v161
	ds_read_b128 v[196:199], v161 offset:1024
	ds_read_b128 v[200:203], v161 offset:2048
	ds_read_b128 v[204:207], v161 offset:3072
	ds_read_b128 v[208:211], v161 offset:4096
	ds_read_b128 v[212:215], v161 offset:5120
	ds_read_b128 v[216:219], v161 offset:6144
	ds_read_b128 v[220:223], v161 offset:7168
	global_load_lds_dwordx4 v[152:153], off
	v_lshl_add_u64 v[152:153], s[44:45], 0, v[144:145]
	s_add_i32 m0, s94, 0xe000
	s_nop 0
	global_load_lds_dwordx4 v[152:153], off
	s_waitcnt vmcnt(8)
	s_waitcnt lgkmcnt(0)
	s_barrier
	s_setprio 1
	s_waitcnt lgkmcnt(0)
	v_mfma_f32_16x16x32_bf16 v[112:115], v[148:151], v[192:195], v[112:115]
	v_mfma_f32_16x16x32_bf16 v[112:115], v[164:167], v[196:199], v[112:115]
	v_mfma_f32_16x16x32_bf16 v[116:119], v[168:171], v[192:195], v[116:119]
	v_mfma_f32_16x16x32_bf16 v[116:119], v[172:175], v[196:199], v[116:119]
	v_mfma_f32_16x16x32_bf16 v[100:103], v[148:151], v[200:203], v[100:103]
	v_mfma_f32_16x16x32_bf16 v[100:103], v[164:167], v[204:207], v[100:103]
	v_mfma_f32_16x16x32_bf16 v[96:99], v[168:171], v[200:203], v[96:99]
	v_mfma_f32_16x16x32_bf16 v[96:99], v[172:175], v[204:207], v[96:99]
	v_mfma_f32_16x16x32_bf16 v[84:87], v[148:151], v[208:211], v[84:87]
	v_mfma_f32_16x16x32_bf16 v[84:87], v[164:167], v[212:215], v[84:87]
	v_mfma_f32_16x16x32_bf16 v[80:83], v[168:171], v[208:211], v[80:83]
	v_mfma_f32_16x16x32_bf16 v[80:83], v[172:175], v[212:215], v[80:83]
	v_mfma_f32_16x16x32_bf16 v[52:55], v[148:151], v[216:219], v[52:55]
	v_mfma_f32_16x16x32_bf16 v[52:55], v[164:167], v[220:223], v[52:55]
	v_mfma_f32_16x16x32_bf16 v[48:51], v[168:171], v[216:219], v[48:51]
	v_mfma_f32_16x16x32_bf16 v[48:51], v[172:175], v[220:223], v[48:51]
	s_setprio 0
	s_setprio 1
	v_mfma_f32_16x16x32_bf16 v[124:127], v[176:179], v[192:195], v[124:127]
	v_mfma_f32_16x16x32_bf16 v[124:127], v[180:183], v[196:199], v[124:127]
	v_mfma_f32_16x16x32_bf16 v[120:123], v[184:187], v[192:195], v[120:123]
	v_mfma_f32_16x16x32_bf16 v[120:123], v[188:191], v[196:199], v[120:123]
	v_mfma_f32_16x16x32_bf16 v[108:111], v[176:179], v[200:203], v[108:111]
	v_mfma_f32_16x16x32_bf16 v[108:111], v[180:183], v[204:207], v[108:111]
	v_mfma_f32_16x16x32_bf16 v[104:107], v[184:187], v[200:203], v[104:107]
	v_mfma_f32_16x16x32_bf16 v[104:107], v[188:191], v[204:207], v[104:107]
	v_mfma_f32_16x16x32_bf16 v[92:95], v[176:179], v[208:211], v[92:95]
	v_mfma_f32_16x16x32_bf16 v[92:95], v[180:183], v[212:215], v[92:95]
	v_mfma_f32_16x16x32_bf16 v[88:91], v[184:187], v[208:211], v[88:91]
	v_mfma_f32_16x16x32_bf16 v[88:91], v[188:191], v[212:215], v[88:91]
	v_mfma_f32_16x16x32_bf16 v[68:71], v[176:179], v[216:219], v[68:71]
	v_mfma_f32_16x16x32_bf16 v[68:71], v[180:183], v[220:223], v[68:71]
	v_mfma_f32_16x16x32_bf16 v[64:67], v[184:187], v[216:219], v[64:67]
	v_mfma_f32_16x16x32_bf16 v[64:67], v[188:191], v[220:223], v[64:67]
	s_setprio 0
	s_barrier
	s_add_i32 s88, s77, s97
	v_lshl_add_u64 v[152:153], s[46:47], 0, v[132:133]
	s_mov_b32 m0, s88
	ds_read_b128 v[192:195], v161 offset:16384
	ds_read_b128 v[196:199], v161 offset:17408
	ds_read_b128 v[200:203], v161 offset:18432
	ds_read_b128 v[204:207], v161 offset:19456
	ds_read_b128 v[208:211], v161 offset:20480
	ds_read_b128 v[212:215], v161 offset:21504
	ds_read_b128 v[216:219], v161 offset:22528
	ds_read_b128 v[220:223], v161 offset:23552
	global_load_lds_dwordx4 v[152:153], off
	s_add_i32 m0, s88, 0x2000
	s_add_u32 s88, s46, 0x100000
	v_lshl_add_u64 v[224:225], s[46:47], 0, v[136:137]
	s_addc_u32 s89, s47, 0
	s_add_i32 s90, s78, s97
	global_load_lds_dwordx4 v[224:225], off
	v_lshl_add_u64 v[226:227], s[88:89], 0, v[132:133]
	s_mov_b32 m0, s90
	v_lshl_add_u64 v[228:229], s[48:49], 0, v[134:135]
	global_load_lds_dwordx4 v[226:227], off
	v_lshl_add_u64 v[226:227], s[88:89], 0, v[136:137]
	s_add_i32 m0, s90, 0x2000
	s_nop 0
	global_load_lds_dwordx4 v[226:227], off
	v_lshl_add_u64 v[226:227], s[48:49], 0, v[130:131]
	s_mov_b32 m0, s94
	s_nop 0
	global_load_lds_dwordx4 v[226:227], off
	s_mov_b32 m0, s52
	s_nop 0
	global_load_lds_dwordx4 v[228:229], off
	s_waitcnt vmcnt(8)
	s_waitcnt lgkmcnt(0)
	s_barrier
	s_setprio 1
	s_waitcnt lgkmcnt(0)
	v_mfma_f32_16x16x32_bf16 v[60:63], v[148:151], v[192:195], v[60:63]
	v_mfma_f32_16x16x32_bf16 v[60:63], v[164:167], v[196:199], v[60:63]
	v_mfma_f32_16x16x32_bf16 v[56:59], v[168:171], v[192:195], v[56:59]
	v_mfma_f32_16x16x32_bf16 v[56:59], v[172:175], v[196:199], v[56:59]
	v_mfma_f32_16x16x32_bf16 v[36:39], v[148:151], v[200:203], v[36:39]
	v_mfma_f32_16x16x32_bf16 v[36:39], v[164:167], v[204:207], v[36:39]
	v_mfma_f32_16x16x32_bf16 v[32:35], v[168:171], v[200:203], v[32:35]
	v_mfma_f32_16x16x32_bf16 v[32:35], v[172:175], v[204:207], v[32:35]
	v_mfma_f32_16x16x32_bf16 v[20:23], v[148:151], v[208:211], v[20:23]
	v_mfma_f32_16x16x32_bf16 v[20:23], v[164:167], v[212:215], v[20:23]
	v_mfma_f32_16x16x32_bf16 v[16:19], v[168:171], v[208:211], v[16:19]
	v_mfma_f32_16x16x32_bf16 v[16:19], v[172:175], v[212:215], v[16:19]
	v_mfma_f32_16x16x32_bf16 v[4:7], v[148:151], v[216:219], v[4:7]
	v_mfma_f32_16x16x32_bf16 v[4:7], v[164:167], v[220:223], v[4:7]
	v_mfma_f32_16x16x32_bf16 v[0:3], v[168:171], v[216:219], v[0:3]
	v_mfma_f32_16x16x32_bf16 v[0:3], v[172:175], v[220:223], v[0:3]
	s_setprio 0
	s_setprio 1
	v_mfma_f32_16x16x32_bf16 v[76:79], v[176:179], v[192:195], v[76:79]
	v_mfma_f32_16x16x32_bf16 v[76:79], v[180:183], v[196:199], v[76:79]
	v_mfma_f32_16x16x32_bf16 v[72:75], v[184:187], v[192:195], v[72:75]
	v_mfma_f32_16x16x32_bf16 v[72:75], v[188:191], v[196:199], v[72:75]
	v_mfma_f32_16x16x32_bf16 v[44:47], v[176:179], v[200:203], v[44:47]
	v_mfma_f32_16x16x32_bf16 v[44:47], v[180:183], v[204:207], v[44:47]
	v_mfma_f32_16x16x32_bf16 v[40:43], v[184:187], v[200:203], v[40:43]
	v_mfma_f32_16x16x32_bf16 v[40:43], v[188:191], v[204:207], v[40:43]
	v_mfma_f32_16x16x32_bf16 v[28:31], v[176:179], v[208:211], v[28:31]
	v_mfma_f32_16x16x32_bf16 v[28:31], v[180:183], v[212:215], v[28:31]
	v_mfma_f32_16x16x32_bf16 v[24:27], v[184:187], v[208:211], v[24:27]
	v_mfma_f32_16x16x32_bf16 v[24:27], v[188:191], v[212:215], v[24:27]
	v_mfma_f32_16x16x32_bf16 v[12:15], v[176:179], v[216:219], v[12:15]
	v_mfma_f32_16x16x32_bf16 v[12:15], v[180:183], v[220:223], v[12:15]
	v_mfma_f32_16x16x32_bf16 v[8:11], v[184:187], v[216:219], v[8:11]
	v_mfma_f32_16x16x32_bf16 v[8:11], v[188:191], v[220:223], v[8:11]
	s_setprio 0
	s_barrier
	s_add_i32 s88, 0, 0x18000
	v_add_u32_e32 v163, s88, v157
	s_add_i32 s89, 0, 0x1c000
	ds_read_b128 v[148:151], v163
	ds_read_b128 v[164:167], v163 offset:1024
	ds_read_b128 v[168:171], v163 offset:2048
	ds_read_b128 v[172:175], v163 offset:3072
	v_add_u32_e32 v163, s89, v157
	ds_read_b128 v[176:179], v163
	ds_read_b128 v[180:183], v163 offset:1024
	ds_read_b128 v[184:187], v163 offset:2048
	ds_read_b128 v[188:191], v163 offset:3072
	s_add_u32 s48, s48, 0x100000
	s_addc_u32 s49, s49, 0
	s_mov_b32 m0, s53
	v_lshl_add_u64 v[230:231], s[48:49], 0, v[130:131]
	ds_read_b128 v[192:195], v161 offset:32768
	ds_read_b128 v[196:199], v161 offset:33792
	ds_read_b128 v[200:203], v161 offset:34816
	ds_read_b128 v[204:207], v161 offset:35840
	ds_read_b128 v[208:211], v161 offset:36864
	ds_read_b128 v[212:215], v161 offset:37888
	ds_read_b128 v[216:219], v161 offset:38912
	ds_read_b128 v[220:223], v161 offset:39936
	global_load_lds_dwordx4 v[230:231], off
	v_lshl_add_u64 v[230:231], s[48:49], 0, v[134:135]
	s_mov_b32 m0, s54
	s_nop 0
	global_load_lds_dwordx4 v[230:231], off
	s_waitcnt vmcnt(8)
	s_waitcnt lgkmcnt(0)
	s_barrier
	s_setprio 1
	s_waitcnt lgkmcnt(0)
	v_mfma_f32_16x16x32_bf16 v[112:115], v[148:151], v[192:195], v[112:115]
	v_mfma_f32_16x16x32_bf16 v[112:115], v[164:167], v[196:199], v[112:115]
	v_mfma_f32_16x16x32_bf16 v[116:119], v[168:171], v[192:195], v[116:119]
	v_mfma_f32_16x16x32_bf16 v[116:119], v[172:175], v[196:199], v[116:119]
	v_mfma_f32_16x16x32_bf16 v[100:103], v[148:151], v[200:203], v[100:103]
	v_mfma_f32_16x16x32_bf16 v[100:103], v[164:167], v[204:207], v[100:103]
	v_mfma_f32_16x16x32_bf16 v[96:99], v[168:171], v[200:203], v[96:99]
	v_mfma_f32_16x16x32_bf16 v[96:99], v[172:175], v[204:207], v[96:99]
	v_mfma_f32_16x16x32_bf16 v[84:87], v[148:151], v[208:211], v[84:87]
	v_mfma_f32_16x16x32_bf16 v[84:87], v[164:167], v[212:215], v[84:87]
	v_mfma_f32_16x16x32_bf16 v[80:83], v[168:171], v[208:211], v[80:83]
	v_mfma_f32_16x16x32_bf16 v[80:83], v[172:175], v[212:215], v[80:83]
	v_mfma_f32_16x16x32_bf16 v[52:55], v[148:151], v[216:219], v[52:55]
	v_mfma_f32_16x16x32_bf16 v[52:55], v[164:167], v[220:223], v[52:55]
	v_mfma_f32_16x16x32_bf16 v[48:51], v[168:171], v[216:219], v[48:51]
	v_mfma_f32_16x16x32_bf16 v[48:51], v[172:175], v[220:223], v[48:51]
	s_setprio 0
	s_setprio 1
	v_mfma_f32_16x16x32_bf16 v[124:127], v[176:179], v[192:195], v[124:127]
	v_mfma_f32_16x16x32_bf16 v[124:127], v[180:183], v[196:199], v[124:127]
	v_mfma_f32_16x16x32_bf16 v[120:123], v[184:187], v[192:195], v[120:123]
	v_mfma_f32_16x16x32_bf16 v[120:123], v[188:191], v[196:199], v[120:123]
	v_mfma_f32_16x16x32_bf16 v[108:111], v[176:179], v[200:203], v[108:111]
	v_mfma_f32_16x16x32_bf16 v[108:111], v[180:183], v[204:207], v[108:111]
	v_mfma_f32_16x16x32_bf16 v[104:107], v[184:187], v[200:203], v[104:107]
	v_mfma_f32_16x16x32_bf16 v[104:107], v[188:191], v[204:207], v[104:107]
	v_mfma_f32_16x16x32_bf16 v[92:95], v[176:179], v[208:211], v[92:95]
	v_mfma_f32_16x16x32_bf16 v[92:95], v[180:183], v[212:215], v[92:95]
	v_mfma_f32_16x16x32_bf16 v[88:91], v[184:187], v[208:211], v[88:91]
	v_mfma_f32_16x16x32_bf16 v[88:91], v[188:191], v[212:215], v[88:91]
	v_mfma_f32_16x16x32_bf16 v[68:71], v[176:179], v[216:219], v[68:71]
	v_mfma_f32_16x16x32_bf16 v[68:71], v[180:183], v[220:223], v[68:71]
	v_mfma_f32_16x16x32_bf16 v[64:67], v[184:187], v[216:219], v[64:67]
	v_mfma_f32_16x16x32_bf16 v[64:67], v[188:191], v[220:223], v[64:67]
	s_setprio 0
	s_barrier
	s_add_i32 s48, s88, s97
	v_lshl_add_u64 v[152:153], v[152:153], 0, s[18:19]
	s_mov_b32 m0, s48
	ds_read_b128 v[192:195], v161 offset:49152
	ds_read_b128 v[196:199], v161 offset:50176
	ds_read_b128 v[200:203], v161 offset:51200
	ds_read_b128 v[204:207], v161 offset:52224
	ds_read_b128 v[208:211], v161 offset:53248
	ds_read_b128 v[212:215], v161 offset:54272
	ds_read_b128 v[216:219], v161 offset:55296
	ds_read_b128 v[220:223], v161 offset:56320
	global_load_lds_dwordx4 v[152:153], off
	s_add_i32 m0, s48, 0x2000
	s_add_u32 s46, s46, 0x100080
	v_lshl_add_u64 v[152:153], v[224:225], 0, s[18:19]
	s_addc_u32 s47, s47, 0
	s_add_i32 s48, s89, s97
	global_load_lds_dwordx4 v[152:153], off
	v_lshl_add_u64 v[152:153], s[46:47], 0, v[132:133]
	s_mov_b32 m0, s48
	s_nop 0
	global_load_lds_dwordx4 v[152:153], off
	v_lshl_add_u64 v[152:153], s[46:47], 0, v[136:137]
	s_add_i32 m0, s48, 0x2000
	s_nop 0
	global_load_lds_dwordx4 v[152:153], off
	v_lshl_add_u64 v[152:153], v[226:227], 0, s[18:19]
	s_mov_b32 m0, s68
	s_nop 0
	global_load_lds_dwordx4 v[152:153], off
	v_lshl_add_u64 v[152:153], v[228:229], 0, s[18:19]
	s_mov_b32 m0, s69
	s_nop 0
	global_load_lds_dwordx4 v[152:153], off
	s_waitcnt vmcnt(8)
	s_waitcnt lgkmcnt(0)
	s_barrier
	s_setprio 1
	s_waitcnt lgkmcnt(0)
	v_mfma_f32_16x16x32_bf16 v[60:63], v[148:151], v[192:195], v[60:63]
	v_mfma_f32_16x16x32_bf16 v[60:63], v[164:167], v[196:199], v[60:63]
	v_mfma_f32_16x16x32_bf16 v[56:59], v[168:171], v[192:195], v[56:59]
	v_mfma_f32_16x16x32_bf16 v[56:59], v[172:175], v[196:199], v[56:59]
	v_mfma_f32_16x16x32_bf16 v[36:39], v[148:151], v[200:203], v[36:39]
	v_mfma_f32_16x16x32_bf16 v[36:39], v[164:167], v[204:207], v[36:39]
	v_mfma_f32_16x16x32_bf16 v[32:35], v[168:171], v[200:203], v[32:35]
	v_mfma_f32_16x16x32_bf16 v[32:35], v[172:175], v[204:207], v[32:35]
	v_mfma_f32_16x16x32_bf16 v[20:23], v[148:151], v[208:211], v[20:23]
	v_mfma_f32_16x16x32_bf16 v[20:23], v[164:167], v[212:215], v[20:23]
	v_mfma_f32_16x16x32_bf16 v[16:19], v[168:171], v[208:211], v[16:19]
	v_mfma_f32_16x16x32_bf16 v[16:19], v[172:175], v[212:215], v[16:19]
	v_mfma_f32_16x16x32_bf16 v[4:7], v[148:151], v[216:219], v[4:7]
	v_mfma_f32_16x16x32_bf16 v[4:7], v[164:167], v[220:223], v[4:7]
	v_mfma_f32_16x16x32_bf16 v[0:3], v[168:171], v[216:219], v[0:3]
	v_mfma_f32_16x16x32_bf16 v[0:3], v[172:175], v[220:223], v[0:3]
	s_setprio 0
	s_setprio 1
	v_mfma_f32_16x16x32_bf16 v[76:79], v[176:179], v[192:195], v[76:79]
	v_mfma_f32_16x16x32_bf16 v[76:79], v[180:183], v[196:199], v[76:79]
	v_mfma_f32_16x16x32_bf16 v[72:75], v[184:187], v[192:195], v[72:75]
	v_mfma_f32_16x16x32_bf16 v[72:75], v[188:191], v[196:199], v[72:75]
	v_mfma_f32_16x16x32_bf16 v[44:47], v[176:179], v[200:203], v[44:47]
	v_mfma_f32_16x16x32_bf16 v[44:47], v[180:183], v[204:207], v[44:47]
	v_mfma_f32_16x16x32_bf16 v[40:43], v[184:187], v[200:203], v[40:43]
	v_mfma_f32_16x16x32_bf16 v[40:43], v[188:191], v[204:207], v[40:43]
	v_mfma_f32_16x16x32_bf16 v[28:31], v[176:179], v[208:211], v[28:31]
	v_mfma_f32_16x16x32_bf16 v[28:31], v[180:183], v[212:215], v[28:31]
	v_mfma_f32_16x16x32_bf16 v[24:27], v[184:187], v[208:211], v[24:27]
	v_mfma_f32_16x16x32_bf16 v[24:27], v[188:191], v[212:215], v[24:27]
	v_mfma_f32_16x16x32_bf16 v[12:15], v[176:179], v[216:219], v[12:15]
	v_mfma_f32_16x16x32_bf16 v[12:15], v[180:183], v[220:223], v[12:15]
	v_mfma_f32_16x16x32_bf16 v[8:11], v[184:187], v[216:219], v[8:11]
	v_mfma_f32_16x16x32_bf16 v[8:11], v[188:191], v[220:223], v[8:11]
	s_setprio 0
	s_barrier
	s_add_u32 s85, s85, 0x100
	s_addc_u32 s86, s86, 0
	s_add_u32 s44, s44, 0x100
	s_addc_u32 s45, s45, 0
	s_cmp_ge_u32 s87, s84
	s_mov_b32 s46, s87
	s_cbranch_scc0 .LBB0_2289
	v_readlane_b32 s44, v254, 27
	v_readlane_b32 s45, v254, 28
	s_and_b64 vcc, exec, s[44:45]
	s_cbranch_vccz .LBB0_2297
	s_barrier
	s_cmp_lt_i32 s16, 0
	s_mov_b64 s[44:45], -1
	s_cbranch_scc1 .LBB0_2298

.LBB0_2453:
	ds_read_b128 v[128:131], v228
	ds_read_b128 v[132:135], v228 offset:1024
	ds_read_b128 v[136:139], v228 offset:2048
	ds_read_b128 v[140:143], v228 offset:3072
	ds_read_b128 v[144:147], v229
	ds_read_b128 v[148:151], v229 offset:1024
	ds_read_b128 v[152:155], v229 offset:2048
	ds_read_b128 v[156:159], v229 offset:3072
	s_add_i32 s79, s46, 2
	s_add_u32 s47, s44, 0xffc00080
	s_addc_u32 s48, s45, -1
	s_cmp_eq_u32 s75, s46
	s_cselect_b32 s46, s43, s77
	s_cselect_b32 s49, s35, s48
	s_cselect_b32 s48, s41, s47
	s_cselect_b32 s47, s31, s78
	v_lshl_add_u64 v[208:209], s[44:45], 0, v[202:203]
	s_add_i32 m0, s94, 0xc000
	ds_read_b128 v[160:163], v230
	ds_read_b128 v[164:167], v230 offset:1024
	ds_read_b128 v[168:171], v230 offset:2048
	ds_read_b128 v[172:175], v230 offset:3072
	ds_read_b128 v[176:179], v230 offset:4096
	ds_read_b128 v[180:183], v230 offset:5120
	ds_read_b128 v[184:187], v230 offset:6144
	ds_read_b128 v[188:191], v230 offset:7168
	global_load_lds_dwordx4 v[208:209], off
	v_lshl_add_u64 v[208:209], s[44:45], 0, v[204:205]
	s_add_i32 m0, s94, 0xe000
	s_nop 0
	global_load_lds_dwordx4 v[208:209], off
	s_waitcnt vmcnt(8)
	s_waitcnt lgkmcnt(0)
	s_barrier
	s_setprio 1
	s_waitcnt lgkmcnt(0)
	v_mfma_f32_16x16x32_bf16 v[112:115], v[128:131], v[160:163], v[112:115]
	v_mfma_f32_16x16x32_bf16 v[112:115], v[132:135], v[164:167], v[112:115]
	v_mfma_f32_16x16x32_bf16 v[116:119], v[136:139], v[160:163], v[116:119]
	v_mfma_f32_16x16x32_bf16 v[116:119], v[140:143], v[164:167], v[116:119]
	v_mfma_f32_16x16x32_bf16 v[100:103], v[128:131], v[168:171], v[100:103]
	v_mfma_f32_16x16x32_bf16 v[100:103], v[132:135], v[172:175], v[100:103]
	v_mfma_f32_16x16x32_bf16 v[96:99], v[136:139], v[168:171], v[96:99]
	v_mfma_f32_16x16x32_bf16 v[96:99], v[140:143], v[172:175], v[96:99]
	v_mfma_f32_16x16x32_bf16 v[84:87], v[128:131], v[176:179], v[84:87]
	v_mfma_f32_16x16x32_bf16 v[84:87], v[132:135], v[180:183], v[84:87]
	v_mfma_f32_16x16x32_bf16 v[80:83], v[136:139], v[176:179], v[80:83]
	v_mfma_f32_16x16x32_bf16 v[80:83], v[140:143], v[180:183], v[80:83]
	v_mfma_f32_16x16x32_bf16 v[52:55], v[128:131], v[184:187], v[52:55]
	v_mfma_f32_16x16x32_bf16 v[52:55], v[132:135], v[188:191], v[52:55]
	v_mfma_f32_16x16x32_bf16 v[48:51], v[136:139], v[184:187], v[48:51]
	v_mfma_f32_16x16x32_bf16 v[48:51], v[140:143], v[188:191], v[48:51]
	s_setprio 0
	s_setprio 1
	v_mfma_f32_16x16x32_bf16 v[124:127], v[144:147], v[160:163], v[124:127]
	v_mfma_f32_16x16x32_bf16 v[124:127], v[148:151], v[164:167], v[124:127]
	v_mfma_f32_16x16x32_bf16 v[120:123], v[152:155], v[160:163], v[120:123]
	v_mfma_f32_16x16x32_bf16 v[120:123], v[156:159], v[164:167], v[120:123]
	v_mfma_f32_16x16x32_bf16 v[108:111], v[144:147], v[168:171], v[108:111]
	v_mfma_f32_16x16x32_bf16 v[108:111], v[148:151], v[172:175], v[108:111]
	v_mfma_f32_16x16x32_bf16 v[104:107], v[152:155], v[168:171], v[104:107]
	v_mfma_f32_16x16x32_bf16 v[104:107], v[156:159], v[172:175], v[104:107]
	v_mfma_f32_16x16x32_bf16 v[92:95], v[144:147], v[176:179], v[92:95]
	v_mfma_f32_16x16x32_bf16 v[92:95], v[148:151], v[180:183], v[92:95]
	v_mfma_f32_16x16x32_bf16 v[88:91], v[152:155], v[176:179], v[88:91]
	v_mfma_f32_16x16x32_bf16 v[88:91], v[156:159], v[180:183], v[88:91]
	v_mfma_f32_16x16x32_bf16 v[68:71], v[144:147], v[184:187], v[68:71]
	v_mfma_f32_16x16x32_bf16 v[68:71], v[148:151], v[188:191], v[68:71]
	v_mfma_f32_16x16x32_bf16 v[64:67], v[152:155], v[184:187], v[64:67]
	v_mfma_f32_16x16x32_bf16 v[64:67], v[156:159], v[188:191], v[64:67]
	s_setprio 0
	s_barrier
	s_add_i32 s80, s68, s97
	v_lshl_add_u64 v[208:209], s[46:47], 0, v[194:195]
	s_mov_b32 m0, s80
	ds_read_b128 v[160:163], v230 offset:16384
	ds_read_b128 v[164:167], v230 offset:17408
	ds_read_b128 v[168:171], v230 offset:18432
	ds_read_b128 v[172:175], v230 offset:19456
	ds_read_b128 v[176:179], v230 offset:20480
	ds_read_b128 v[180:183], v230 offset:21504
	ds_read_b128 v[184:187], v230 offset:22528
	ds_read_b128 v[188:191], v230 offset:23552
	global_load_lds_dwordx4 v[208:209], off
	s_add_i32 m0, s80, 0x2000
	s_add_u32 s80, s46, 0x400000
	v_lshl_add_u64 v[210:211], s[46:47], 0, v[198:199]
	s_addc_u32 s81, s47, 0
	s_add_i32 s84, s69, s97
	global_load_lds_dwordx4 v[210:211], off
	v_lshl_add_u64 v[212:213], s[80:81], 0, v[194:195]
	s_mov_b32 m0, s84
	v_lshl_add_u64 v[214:215], s[48:49], 0, v[196:197]
	global_load_lds_dwordx4 v[212:213], off
	v_lshl_add_u64 v[212:213], s[80:81], 0, v[198:199]
	s_add_i32 m0, s84, 0x2000
	s_nop 0
	global_load_lds_dwordx4 v[212:213], off
	v_lshl_add_u64 v[212:213], s[48:49], 0, v[192:193]
	s_mov_b32 m0, s94
	s_nop 0
	global_load_lds_dwordx4 v[212:213], off
	s_mov_b32 m0, s51
	s_nop 0
	global_load_lds_dwordx4 v[214:215], off
	s_waitcnt vmcnt(8)
	s_waitcnt lgkmcnt(0)
	s_barrier
	s_setprio 1
	s_waitcnt lgkmcnt(0)
	v_mfma_f32_16x16x32_bf16 v[60:63], v[128:131], v[160:163], v[60:63]
	v_mfma_f32_16x16x32_bf16 v[60:63], v[132:135], v[164:167], v[60:63]
	v_mfma_f32_16x16x32_bf16 v[56:59], v[136:139], v[160:163], v[56:59]
	v_mfma_f32_16x16x32_bf16 v[56:59], v[140:143], v[164:167], v[56:59]
	v_mfma_f32_16x16x32_bf16 v[36:39], v[128:131], v[168:171], v[36:39]
	v_mfma_f32_16x16x32_bf16 v[36:39], v[132:135], v[172:175], v[36:39]
	v_mfma_f32_16x16x32_bf16 v[32:35], v[136:139], v[168:171], v[32:35]
	v_mfma_f32_16x16x32_bf16 v[32:35], v[140:143], v[172:175], v[32:35]
	v_mfma_f32_16x16x32_bf16 v[20:23], v[128:131], v[176:179], v[20:23]
	v_mfma_f32_16x16x32_bf16 v[20:23], v[132:135], v[180:183], v[20:23]
	v_mfma_f32_16x16x32_bf16 v[16:19], v[136:139], v[176:179], v[16:19]
	v_mfma_f32_16x16x32_bf16 v[16:19], v[140:143], v[180:183], v[16:19]
	v_mfma_f32_16x16x32_bf16 v[4:7], v[128:131], v[184:187], v[4:7]
	v_mfma_f32_16x16x32_bf16 v[4:7], v[132:135], v[188:191], v[4:7]
	v_mfma_f32_16x16x32_bf16 v[0:3], v[136:139], v[184:187], v[0:3]
	v_mfma_f32_16x16x32_bf16 v[0:3], v[140:143], v[188:191], v[0:3]
	s_setprio 0
	s_setprio 1
	v_mfma_f32_16x16x32_bf16 v[76:79], v[144:147], v[160:163], v[76:79]
	v_mfma_f32_16x16x32_bf16 v[76:79], v[148:151], v[164:167], v[76:79]
	v_mfma_f32_16x16x32_bf16 v[72:75], v[152:155], v[160:163], v[72:75]
	v_mfma_f32_16x16x32_bf16 v[72:75], v[156:159], v[164:167], v[72:75]
	v_mfma_f32_16x16x32_bf16 v[44:47], v[144:147], v[168:171], v[44:47]
	v_mfma_f32_16x16x32_bf16 v[44:47], v[148:151], v[172:175], v[44:47]
	v_mfma_f32_16x16x32_bf16 v[40:43], v[152:155], v[168:171], v[40:43]
	v_mfma_f32_16x16x32_bf16 v[40:43], v[156:159], v[172:175], v[40:43]
	v_mfma_f32_16x16x32_bf16 v[28:31], v[144:147], v[176:179], v[28:31]
	v_mfma_f32_16x16x32_bf16 v[28:31], v[148:151], v[180:183], v[28:31]
	v_mfma_f32_16x16x32_bf16 v[24:27], v[152:155], v[176:179], v[24:27]
	v_mfma_f32_16x16x32_bf16 v[24:27], v[156:159], v[180:183], v[24:27]
	v_mfma_f32_16x16x32_bf16 v[12:15], v[144:147], v[184:187], v[12:15]
	v_mfma_f32_16x16x32_bf16 v[12:15], v[148:151], v[188:191], v[12:15]
	v_mfma_f32_16x16x32_bf16 v[8:11], v[152:155], v[184:187], v[8:11]
	v_mfma_f32_16x16x32_bf16 v[8:11], v[156:159], v[188:191], v[8:11]
	s_setprio 0
	s_barrier
	s_add_i32 s80, 0, 0x18000
	s_add_i32 s81, 0, 0x1c000
	v_add_u32_e32 v140, s80, v226
	v_add_u32_e32 v156, s81, v226
	ds_read_b128 v[128:131], v140
	ds_read_b128 v[132:135], v140 offset:1024
	ds_read_b128 v[136:139], v140 offset:2048
	ds_read_b128 v[140:143], v140 offset:3072
	ds_read_b128 v[144:147], v156
	ds_read_b128 v[148:151], v156 offset:1024
	ds_read_b128 v[152:155], v156 offset:2048
	ds_read_b128 v[156:159], v156 offset:3072
	s_add_u32 s48, s48, 0x400000
	s_addc_u32 s49, s49, 0
	s_mov_b32 m0, s52
	v_lshl_add_u64 v[216:217], s[48:49], 0, v[192:193]
	ds_read_b128 v[160:163], v230 offset:32768
	ds_read_b128 v[164:167], v230 offset:33792
	ds_read_b128 v[168:171], v230 offset:34816
	ds_read_b128 v[172:175], v230 offset:35840
	ds_read_b128 v[176:179], v230 offset:36864
	ds_read_b128 v[180:183], v230 offset:37888
	ds_read_b128 v[184:187], v230 offset:38912
	ds_read_b128 v[188:191], v230 offset:39936
	global_load_lds_dwordx4 v[216:217], off
	v_lshl_add_u64 v[216:217], s[48:49], 0, v[196:197]
	s_mov_b32 m0, s53
	s_nop 0
	global_load_lds_dwordx4 v[216:217], off
	s_waitcnt vmcnt(8)
	s_waitcnt lgkmcnt(0)
	s_barrier
	s_setprio 1
	s_waitcnt lgkmcnt(0)
	v_mfma_f32_16x16x32_bf16 v[112:115], v[128:131], v[160:163], v[112:115]
	v_mfma_f32_16x16x32_bf16 v[112:115], v[132:135], v[164:167], v[112:115]
	v_mfma_f32_16x16x32_bf16 v[116:119], v[136:139], v[160:163], v[116:119]
	v_mfma_f32_16x16x32_bf16 v[116:119], v[140:143], v[164:167], v[116:119]
	v_mfma_f32_16x16x32_bf16 v[100:103], v[128:131], v[168:171], v[100:103]
	v_mfma_f32_16x16x32_bf16 v[100:103], v[132:135], v[172:175], v[100:103]
	v_mfma_f32_16x16x32_bf16 v[96:99], v[136:139], v[168:171], v[96:99]
	v_mfma_f32_16x16x32_bf16 v[96:99], v[140:143], v[172:175], v[96:99]
	v_mfma_f32_16x16x32_bf16 v[84:87], v[128:131], v[176:179], v[84:87]
	v_mfma_f32_16x16x32_bf16 v[84:87], v[132:135], v[180:183], v[84:87]
	v_mfma_f32_16x16x32_bf16 v[80:83], v[136:139], v[176:179], v[80:83]
	v_mfma_f32_16x16x32_bf16 v[80:83], v[140:143], v[180:183], v[80:83]
	v_mfma_f32_16x16x32_bf16 v[52:55], v[128:131], v[184:187], v[52:55]
	v_mfma_f32_16x16x32_bf16 v[52:55], v[132:135], v[188:191], v[52:55]
	v_mfma_f32_16x16x32_bf16 v[48:51], v[136:139], v[184:187], v[48:51]
	v_mfma_f32_16x16x32_bf16 v[48:51], v[140:143], v[188:191], v[48:51]
	s_setprio 0
	s_setprio 1
	v_mfma_f32_16x16x32_bf16 v[124:127], v[144:147], v[160:163], v[124:127]
	v_mfma_f32_16x16x32_bf16 v[124:127], v[148:151], v[164:167], v[124:127]
	v_mfma_f32_16x16x32_bf16 v[120:123], v[152:155], v[160:163], v[120:123]
	v_mfma_f32_16x16x32_bf16 v[120:123], v[156:159], v[164:167], v[120:123]
	v_mfma_f32_16x16x32_bf16 v[108:111], v[144:147], v[168:171], v[108:111]
	v_mfma_f32_16x16x32_bf16 v[108:111], v[148:151], v[172:175], v[108:111]
	v_mfma_f32_16x16x32_bf16 v[104:107], v[152:155], v[168:171], v[104:107]
	v_mfma_f32_16x16x32_bf16 v[104:107], v[156:159], v[172:175], v[104:107]
	v_mfma_f32_16x16x32_bf16 v[92:95], v[144:147], v[176:179], v[92:95]
	v_mfma_f32_16x16x32_bf16 v[92:95], v[148:151], v[180:183], v[92:95]
	v_mfma_f32_16x16x32_bf16 v[88:91], v[152:155], v[176:179], v[88:91]
	v_mfma_f32_16x16x32_bf16 v[88:91], v[156:159], v[180:183], v[88:91]
	v_mfma_f32_16x16x32_bf16 v[68:71], v[144:147], v[184:187], v[68:71]
	v_mfma_f32_16x16x32_bf16 v[68:71], v[148:151], v[188:191], v[68:71]
	v_mfma_f32_16x16x32_bf16 v[64:67], v[152:155], v[184:187], v[64:67]
	v_mfma_f32_16x16x32_bf16 v[64:67], v[156:159], v[188:191], v[64:67]
	s_setprio 0
	s_barrier
	s_add_i32 s48, s80, s97
	v_lshl_add_u64 v[208:209], v[208:209], 0, s[12:13]
	s_mov_b32 m0, s48
	ds_read_b128 v[160:163], v230 offset:49152
	ds_read_b128 v[164:167], v230 offset:50176
	ds_read_b128 v[168:171], v230 offset:51200
	ds_read_b128 v[172:175], v230 offset:52224
	ds_read_b128 v[176:179], v230 offset:53248
	ds_read_b128 v[180:183], v230 offset:54272
	ds_read_b128 v[184:187], v230 offset:55296
	ds_read_b128 v[188:191], v230 offset:56320
	global_load_lds_dwordx4 v[208:209], off
	s_add_i32 m0, s48, 0x2000
	s_add_u32 s46, s46, 0x400080
	v_lshl_add_u64 v[208:209], v[210:211], 0, s[12:13]
	s_addc_u32 s47, s47, 0
	s_add_i32 s48, s81, s97
	global_load_lds_dwordx4 v[208:209], off
	v_lshl_add_u64 v[208:209], s[46:47], 0, v[194:195]
	s_mov_b32 m0, s48
	s_nop 0
	global_load_lds_dwordx4 v[208:209], off
	v_lshl_add_u64 v[208:209], s[46:47], 0, v[198:199]
	s_add_i32 m0, s48, 0x2000
	s_nop 0
	global_load_lds_dwordx4 v[208:209], off
	v_lshl_add_u64 v[208:209], v[212:213], 0, s[12:13]
	s_mov_b32 m0, s54
	s_nop 0
	global_load_lds_dwordx4 v[208:209], off
	v_lshl_add_u64 v[208:209], v[214:215], 0, s[12:13]
	s_mov_b32 m0, s55
	s_nop 0
	global_load_lds_dwordx4 v[208:209], off
	s_waitcnt vmcnt(8)
	s_waitcnt lgkmcnt(0)
	s_barrier
	s_setprio 1
	s_waitcnt lgkmcnt(0)
	v_mfma_f32_16x16x32_bf16 v[60:63], v[128:131], v[160:163], v[60:63]
	v_mfma_f32_16x16x32_bf16 v[60:63], v[132:135], v[164:167], v[60:63]
	v_mfma_f32_16x16x32_bf16 v[56:59], v[136:139], v[160:163], v[56:59]
	v_mfma_f32_16x16x32_bf16 v[56:59], v[140:143], v[164:167], v[56:59]
	v_mfma_f32_16x16x32_bf16 v[36:39], v[128:131], v[168:171], v[36:39]
	v_mfma_f32_16x16x32_bf16 v[36:39], v[132:135], v[172:175], v[36:39]
	v_mfma_f32_16x16x32_bf16 v[32:35], v[136:139], v[168:171], v[32:35]
	v_mfma_f32_16x16x32_bf16 v[32:35], v[140:143], v[172:175], v[32:35]
	v_mfma_f32_16x16x32_bf16 v[20:23], v[128:131], v[176:179], v[20:23]
	v_mfma_f32_16x16x32_bf16 v[20:23], v[132:135], v[180:183], v[20:23]
	v_mfma_f32_16x16x32_bf16 v[16:19], v[136:139], v[176:179], v[16:19]
	v_mfma_f32_16x16x32_bf16 v[16:19], v[140:143], v[180:183], v[16:19]
	v_mfma_f32_16x16x32_bf16 v[4:7], v[128:131], v[184:187], v[4:7]
	v_mfma_f32_16x16x32_bf16 v[4:7], v[132:135], v[188:191], v[4:7]
	v_mfma_f32_16x16x32_bf16 v[0:3], v[136:139], v[184:187], v[0:3]
	v_mfma_f32_16x16x32_bf16 v[0:3], v[140:143], v[188:191], v[0:3]
	s_setprio 0
	s_setprio 1
	v_mfma_f32_16x16x32_bf16 v[76:79], v[144:147], v[160:163], v[76:79]
	v_mfma_f32_16x16x32_bf16 v[76:79], v[148:151], v[164:167], v[76:79]
	v_mfma_f32_16x16x32_bf16 v[72:75], v[152:155], v[160:163], v[72:75]
	v_mfma_f32_16x16x32_bf16 v[72:75], v[156:159], v[164:167], v[72:75]
	v_mfma_f32_16x16x32_bf16 v[44:47], v[144:147], v[168:171], v[44:47]
	v_mfma_f32_16x16x32_bf16 v[44:47], v[148:151], v[172:175], v[44:47]
	v_mfma_f32_16x16x32_bf16 v[40:43], v[152:155], v[168:171], v[40:43]
	v_mfma_f32_16x16x32_bf16 v[40:43], v[156:159], v[172:175], v[40:43]
	v_mfma_f32_16x16x32_bf16 v[28:31], v[144:147], v[176:179], v[28:31]
	v_mfma_f32_16x16x32_bf16 v[28:31], v[148:151], v[180:183], v[28:31]
	v_mfma_f32_16x16x32_bf16 v[24:27], v[152:155], v[176:179], v[24:27]
	v_mfma_f32_16x16x32_bf16 v[24:27], v[156:159], v[180:183], v[24:27]
	v_mfma_f32_16x16x32_bf16 v[12:15], v[144:147], v[184:187], v[12:15]
	v_mfma_f32_16x16x32_bf16 v[12:15], v[148:151], v[188:191], v[12:15]
	v_mfma_f32_16x16x32_bf16 v[8:11], v[152:155], v[184:187], v[8:11]
	v_mfma_f32_16x16x32_bf16 v[8:11], v[156:159], v[188:191], v[8:11]
	s_setprio 0
	s_barrier
	s_add_u32 s77, s77, 0x100
	s_addc_u32 s78, s78, 0
	s_add_u32 s44, s44, 0x100
	s_addc_u32 s45, s45, 0
	s_cmp_ge_u32 s79, s76
	s_mov_b32 s46, s79
	s_cbranch_scc0 .LBB0_2453
	v_readlane_b32 s44, v254, 27
	v_readlane_b32 s45, v254, 28
	s_and_b64 vcc, exec, s[44:45]
	s_cbranch_vccz .LBB0_2461
	s_barrier
	s_cmp_lt_i32 s10, 0
	s_mov_b64 s[44:45], -1
	s_cbranch_scc1 .LBB0_2462
